# attention work queues: the wait for the next-unit claim atomic moved from right behind the atomic (unit start) to the publish point at the unit's end (vmcnt(8), the atomic is older than the 8 output s
# baseline (speedup 1.0000x reference)
.LBB0_480:
	s_or_b64 exec, exec, s[0:1]
	v_readlane_b32 s0, v243, 55
	s_waitcnt vmcnt(0) lgkmcnt(0)
	s_barrier
	v_mov_b32_e32 v1, s0
	ds_read_b32 v1, v1
	v_readlane_b32 s0, v243, 51
	s_waitcnt lgkmcnt(0)
	s_barrier
	v_cmp_le_i32_e32 vcc, s0, v1
	v_readfirstlane_b32 s11, v1
	s_cbranch_vccnz .LBB0_631
	v_mov_b32_e32 v1, 0
	s_and_saveexec_b64 s[0:1], s[36:37]
	s_cbranch_execz .LBB0_485
	s_mov_b64 s[4:5], exec
	v_mbcnt_lo_u32_b32 v1, s4, 0
	v_mbcnt_hi_u32_b32 v1, s5, v1
	v_cmp_eq_u32_e32 vcc, 0, v1
	s_and_saveexec_b64 s[2:3], vcc
	s_cbranch_execz .LBB0_484
	s_bcnt1_i32_b64 s4, s[4:5]
	v_mov_b32_e32 v2, s4
	v_readlane_b32 s4, v242, 6
	v_readlane_b32 s5, v242, 7
	s_nop 4
	global_atomic_add v247, v163, v2, s[4:5] sc0
.LBB0_484:
	s_or_b64 exec, exec, s[2:3]
.LBB0_485:
	s_or_b64 exec, exec, s[0:1]
	s_abs_i32 s0, s11
	v_readlane_b32 s1, v243, 0
	s_mul_hi_u32 s1, s0, s1
	v_readlane_b32 s4, v243, 53
	s_mul_i32 s2, s1, s4
	s_sub_i32 s0, s0, s2
	s_ashr_i32 s8, s11, 31
	s_add_i32 s2, s1, 1
	s_sub_i32 s3, s0, s4
	s_cmp_ge_u32 s0, s4
	s_cselect_b32 s1, s2, s1
	s_cselect_b32 s0, s3, s0
	s_add_i32 s2, s1, 1
	s_cmp_ge_u32 s0, s4
	s_cselect_b32 s0, s2, s1
	s_xor_b32 s9, s0, s8
	s_sub_i32 s13, s9, s8
	s_mul_i32 s0, s13, s4
	s_sub_i32 s0, s11, s0
	v_readlane_b32 s1, v243, 54
	s_add_i32 s1, s0, s1
	s_mul_hi_i32 s0, s1, 0x2aaaaaab
	s_lshr_b32 s2, s0, 31
	s_add_i32 s0, s0, s2
	s_mul_i32 s2, s0, 6
	s_sub_i32 s18, s1, s2
	s_ashr_i32 s1, s0, 31
	s_lshl_b64 s[2:3], s[0:1], 11
	s_lshl_b32 s1, s13, 8
	s_sub_i32 s11, 0x700, s1
	s_ashr_i32 s1, s11, 31
	s_add_u32 s4, s2, s11
	s_addc_u32 s5, s3, s1
	s_mul_i32 s1, s5, 0x3000
	s_mul_hi_u32 s2, s4, 0x3000
	s_add_i32 s2, s2, s1
	s_mul_i32 s1, s4, 0x3000
	v_readlane_b32 s20, v245, 14
	s_add_u32 s1, s20, s1
	v_readlane_b32 s21, v245, 15
	s_addc_u32 s19, s21, s2
	s_lshl_b32 s2, s18, 7
	s_ashr_i32 s3, s2, 31
	s_lshl_b64 s[34:35], s[2:3], 1
	s_add_u32 s22, s1, s34
	s_addc_u32 s23, s19, s35
	s_mul_hi_i32 s1, s0, 0x1800000
	s_mul_i32 s0, s0, 0x1800000
	s_add_u32 s0, s20, s0
	v_mov_b32_e32 v152, v0
	s_addc_u32 s1, s21, s1
	s_add_u32 s2, s0, s34
	v_ashrrev_i32_e32 v4, 4, v152
	v_and_b32_e32 v5, 0xfffff0, v4
	v_lshlrev_b32_e32 v6, 1, v4
	s_addc_u32 s3, s1, s35
	v_lshlrev_b32_e32 v2, 3, v152
	v_and_or_b32 v5, v6, 8, v5
	v_lshrrev_b32_e32 v6, 1, v4
	v_and_b32_e32 v7, 3, v4
	s_add_u32 s0, s2, 0x1200
	v_and_b32_e32 v3, 0x78, v2
	v_and_or_b32 v6, v6, 4, v7
	v_add_u32_e32 v60, 32, v4
	s_addc_u32 s1, s3, 0
	v_lshlrev_b32_e32 v8, 6, v6
	v_lshlrev_b32_e32 v162, 1, v3
	v_and_b32_e32 v3, 0xfffff0, v60
	v_lshlrev_b32_e32 v6, 1, v60
	s_add_u32 s2, s2, 0x1800
	v_and_or_b32 v3, v6, 8, v3
	s_addc_u32 s3, s3, 0
	s_lshl_b32 s19, s13, 2
	v_readfirstlane_b32 s13, v152
	v_lshrrev_b32_e32 v5, 1, v5
	v_bfe_u32 v2, v2, 5, 2
	v_lshrrev_b32_e32 v3, 1, v3
	s_ashr_i32 s25, s13, 6
	v_or_b32_e32 v5, v5, v2
	v_or_b32_e32 v2, v3, v2
	v_and_b32_e32 v154, 31, v152
	v_and_b32_e32 v9, 48, v162
	v_lshlrev_b32_e32 v2, 9, v2
	s_lshl_b32 s28, s25, 5
	s_sub_i32 s18, 32, s19
	v_bfe_u32 v155, v152, 5, 1
	v_or3_b32 v156, v2, v8, v9
	v_or_b32_e32 v6, s28, v154
	v_mov_b64_e32 v[2:3], s[22:23]
	s_sub_i32 s19, 28, s19
	v_lshlrev_b32_e32 v5, 9, v5
	v_mad_i64_i32 v[6:7], s[20:21], v6, s33, v[2:3]
	v_lshlrev_b32_e32 v2, 4, v155
	v_mov_b32_e32 v3, v163
	s_lshl_b32 s19, s19, 6
	v_lshl_add_u64 v[6:7], v[6:7], 0, v[2:3]
	v_or3_b32 v157, v5, v8, v9
	v_add_u32_e32 v5, s19, v4
	v_add_u32_e32 v18, s19, v60
	s_lshl_b32 s19, s18, 6
	global_load_dwordx4 v[98:101], v[6:7], off offset:3072
	global_load_dwordx4 v[102:105], v[6:7], off offset:3104
	global_load_dwordx4 v[106:109], v[6:7], off offset:3136
	global_load_dwordx4 v[110:113], v[6:7], off offset:3168
	global_load_dwordx4 v[114:117], v[6:7], off offset:3200
	global_load_dwordx4 v[118:121], v[6:7], off offset:3232
	global_load_dwordx4 v[122:125], v[6:7], off offset:3264
	global_load_dwordx4 v[126:129], v[6:7], off offset:3296
	v_mov_b64_e32 v[58:59], s[2:3]
	v_mov_b64_e32 v[66:67], s[0:1]
	s_add_i32 s22, s19, 0xffffff40
	v_mad_i64_i32 v[6:7], s[20:21], v5, s33, v[58:59]
	v_mad_i64_i32 v[14:15], s[20:21], v5, s33, v[66:67]
	v_add_u32_e32 v5, s22, v4
	v_add_u32_e32 v34, s22, v60
	s_add_i32 s22, s19, 0xffffff80
	v_and_b32_e32 v10, 0x70, v152
	v_lshlrev_b32_e32 v3, 8, v4
	v_mad_i64_i32 v[22:23], s[20:21], v5, s33, v[58:59]
	v_mad_i64_i32 v[30:31], s[20:21], v5, s33, v[66:67]
	v_add_u32_e32 v5, s22, v4
	s_sub_i32 s19, s19, 64
	v_bitop3_b32 v3, v162, v3, v10 bitop3:0xde
	v_lshl_add_u64 v[6:7], v[6:7], 0, v[162:163]
	v_mad_i64_i32 v[10:11], s[20:21], v18, s33, v[58:59]
	v_lshl_add_u64 v[14:15], v[14:15], 0, v[162:163]
	v_mad_i64_i32 v[18:19], s[20:21], v18, s33, v[66:67]
	v_mad_i64_i32 v[38:39], s[20:21], v5, s33, v[58:59]
	v_mad_i64_i32 v[46:47], s[20:21], v5, s33, v[66:67]
	v_add_u32_e32 v5, s19, v4
	global_load_dwordx4 v[6:9], v[6:7], off
	v_lshl_add_u64 v[10:11], v[10:11], 0, v[162:163]
	global_load_dwordx4 v[14:17], v[14:15], off
	v_lshl_add_u64 v[18:19], v[18:19], 0, v[162:163]
	v_mad_i64_i32 v[26:27], s[20:21], v34, s33, v[58:59]
	v_lshl_add_u64 v[30:31], v[30:31], 0, v[162:163]
	v_mad_i64_i32 v[34:35], s[20:21], v34, s33, v[66:67]
	v_add_u32_e32 v50, s22, v60
	v_add_u32_e32 v68, s19, v60
	v_mad_i64_i32 v[62:63], s[20:21], v5, s33, v[66:67]
	global_load_dwordx4 v[10:13], v[10:11], off
	v_lshl_add_u64 v[34:35], v[34:35], 0, v[162:163]
	global_load_dwordx4 v[18:21], v[18:19], off
	v_mad_i64_i32 v[42:43], s[20:21], v50, s33, v[58:59]
	global_load_dwordx4 v[30:33], v[30:31], off
	v_lshl_add_u64 v[46:47], v[46:47], 0, v[162:163]
	v_mad_i64_i32 v[50:51], s[20:21], v50, s33, v[66:67]
	v_lshl_add_u64 v[62:63], v[62:63], 0, v[162:163]
	v_mad_i64_i32 v[66:67], s[20:21], v68, s33, v[66:67]
	v_lshl_add_u64 v[22:23], v[22:23], 0, v[162:163]
	global_load_dwordx4 v[34:37], v[34:35], off
	v_lshl_add_u64 v[50:51], v[50:51], 0, v[162:163]
	global_load_dwordx4 v[46:49], v[46:47], off
	v_mad_i64_i32 v[54:55], s[20:21], v5, s33, v[58:59]
	global_load_dwordx4 v[62:65], v[62:63], off
	v_lshl_add_u64 v[66:67], v[66:67], 0, v[162:163]
	global_load_dwordx4 v[22:25], v[22:23], off
	v_lshl_add_u64 v[26:27], v[26:27], 0, v[162:163]
	v_lshl_add_u64 v[38:39], v[38:39], 0, v[162:163]
	global_load_dwordx4 v[50:53], v[50:51], off
	v_lshl_add_u64 v[54:55], v[54:55], 0, v[162:163]
	v_mad_i64_i32 v[58:59], s[20:21], v68, s33, v[58:59]
	global_load_dwordx4 v[66:69], v[66:67], off
	v_lshl_add_u64 v[42:43], v[42:43], 0, v[162:163]
	global_load_dwordx4 v[26:29], v[26:27], off
	v_lshl_add_u64 v[58:59], v[58:59], 0, v[162:163]
	global_load_dwordx4 v[38:41], v[38:39], off
	v_add_u32_e32 v3, 0, v3
	global_load_dwordx4 v[54:57], v[54:55], off
	v_add_u32_e32 v158, 0x10000, v3
	global_load_dwordx4 v[42:45], v[42:43], off
	v_add_u32_e32 v5, 0, v157
	global_load_dwordx4 v[58:61], v[58:59], off
	s_waitcnt vmcnt(14)
	ds_write_b128 v158, v[14:17]
	s_waitcnt vmcnt(12)
	ds_write_b128 v158, v[18:21] offset:8192
	ds_write_b128 v5, v[6:9]
	v_add_u32_e32 v6, 0, v156
	v_add_u32_e32 v7, 0x14000, v3
	v_and_b32_e32 v153, 63, v152
	ds_write_b128 v6, v[10:13]
	s_waitcnt vmcnt(11)
	ds_write_b128 v7, v[30:33]
	s_waitcnt vmcnt(10)
	ds_write_b128 v7, v[34:37] offset:8192
	s_waitcnt vmcnt(7)
	ds_write_b128 v5, v[22:25] offset:16384
	s_waitcnt vmcnt(4)
	ds_write_b128 v6, v[26:29] offset:16384
	v_add_u32_e32 v7, 0x18000, v3
	v_add_u32_e32 v3, 0x1c000, v3
	s_cmp_lt_i32 s18, 1
	ds_write_b128 v7, v[46:49]
	ds_write_b128 v7, v[50:53] offset:8192
	s_waitcnt vmcnt(3)
	ds_write_b128 v5, v[38:41] offset:32768
	s_waitcnt vmcnt(1)
	ds_write_b128 v6, v[42:45] offset:32768
	ds_write_b128 v3, v[62:65]
	ds_write_b128 v3, v[66:69] offset:8192
	ds_write_b128 v5, v[54:57] offset:49152
	s_waitcnt vmcnt(0)
	ds_write_b128 v6, v[58:61] offset:49152
	s_waitcnt lgkmcnt(0)
	s_barrier
	s_cbranch_scc1 .LBB0_501
	v_lshl_add_u64 v[148:149], s[0:1], 0, v[162:163]
	s_lshl_b32 s0, s25, 2
	s_add_i32 s29, s0, 0
	s_add_i32 s0, 0, 0x10000
	v_lshlrev_b32_e32 v8, 4, v154
	v_lshl_add_u32 v159, v154, 8, s0
	s_movk_i32 s0, 0x70
	v_lshlrev_b32_e32 v6, 3, v153
	v_and_b32_e32 v9, 0x70, v8
	v_bitop3_b32 v160, v2, v8, s0 bitop3:0x78
	s_movk_i32 s0, 0x60
	v_lshlrev_b32_e32 v3, 1, v153
	v_lshlrev_b32_e32 v5, 4, v153
	v_and_b32_e32 v6, 0x118, v6
	v_bitop3_b32 v164, v2, v9, s0 bitop3:0x36
	s_lshl_b32 s0, s8, 16
	s_lshl_b32 s1, s9, 16
	s_add_i32 s27, s28, s11
	v_lshl_add_u64 v[146:147], s[2:3], 0, v[162:163]
	v_and_b32_e32 v5, 0xc0, v5
	v_bitop3_b32 v161, v2, v9, 32 bitop3:0x36
	v_bitop3_b32 v162, v2, v9, 64 bitop3:0x36
	v_and_or_b32 v2, v3, 32, v6
	s_sub_i32 s11, s0, s1
	s_lshl_b32 s1, s8, 2
	s_lshl_b32 s2, s9, 2
	s_ashr_i32 s18, s13, 7
	v_lshlrev_b32_e32 v7, 2, v155
	v_add3_u32 v165, v5, 0, v2
	s_sub_i32 s1, s1, s2
	v_add3_u32 v2, s28, -1, v154
	s_lshl_b32 s0, s9, 8
	s_add_i32 s20, s1, 27
	v_sub_u32_e32 v2, v2, v7
	s_lshl_b32 s1, s18, 6
	v_subrev_u32_e32 v166, s0, v4
	s_lshl_b32 s13, s18, 14
	v_subrev_u32_e32 v167, s1, v2
	s_sub_i32 s0, s1, s0
	v_mov_b32_e32 v2, 0
	s_add_i32 s29, s29, 0x21000
	v_cmp_gt_u32_e64 s[38:39], 32, v153
	s_mov_b32 s26, 0
	v_cmp_eq_u32_e64 s[40:41], 0, v153
	s_lshl_b32 s19, s8, 8
	s_add_i32 s13, s13, 0x70000
	s_add_i32 s9, s0, 0x73f
	s_mov_b64 s[0:1], 0
	v_mov_b32_e32 v150, 1.0
	v_mov_b32_e32 v3, v2
	v_mov_b32_e32 v4, v2
	v_mov_b32_e32 v5, v2
	v_mov_b32_e32 v6, v2
	v_mov_b32_e32 v7, v2
	v_mov_b32_e32 v8, v2
	v_mov_b32_e32 v9, v2
	v_mov_b32_e32 v10, v2
	v_mov_b32_e32 v11, v2
	v_mov_b32_e32 v12, v2
	v_mov_b32_e32 v13, v2
	v_mov_b32_e32 v14, v2
	v_mov_b32_e32 v15, v2
	v_mov_b32_e32 v16, v2
	v_mov_b32_e32 v17, v2
	v_mov_b32_e32 v18, v2
	v_mov_b32_e32 v19, v2
	v_mov_b32_e32 v20, v2
	v_mov_b32_e32 v21, v2
	v_mov_b32_e32 v22, v2
	v_mov_b32_e32 v23, v2
	v_mov_b32_e32 v24, v2
	v_mov_b32_e32 v25, v2
	v_mov_b32_e32 v26, v2
	v_mov_b32_e32 v27, v2
	v_mov_b32_e32 v28, v2
	v_mov_b32_e32 v29, v2
	v_mov_b32_e32 v30, v2
	v_mov_b32_e32 v31, v2
	v_mov_b32_e32 v32, v2
	v_mov_b32_e32 v33, v2
	v_mov_b32_e32 v34, v2
	v_mov_b32_e32 v35, v2
	v_mov_b32_e32 v36, v2
	v_mov_b32_e32 v37, v2
	v_mov_b32_e32 v38, v2
	v_mov_b32_e32 v39, v2
	v_mov_b32_e32 v40, v2
	v_mov_b32_e32 v41, v2
	v_mov_b32_e32 v42, v2
	v_mov_b32_e32 v43, v2
	v_mov_b32_e32 v44, v2
	v_mov_b32_e32 v45, v2
	v_mov_b32_e32 v46, v2
	v_mov_b32_e32 v47, v2
	v_mov_b32_e32 v48, v2
	v_mov_b32_e32 v49, v2
	v_mov_b32_e32 v50, v2
	v_mov_b32_e32 v51, v2
	v_mov_b32_e32 v52, v2
	v_mov_b32_e32 v53, v2
	v_mov_b32_e32 v54, v2
	v_mov_b32_e32 v55, v2
	v_mov_b32_e32 v56, v2
	v_mov_b32_e32 v57, v2
	v_mov_b32_e32 v58, v2
	v_mov_b32_e32 v59, v2
	v_mov_b32_e32 v60, v2
	v_mov_b32_e32 v61, v2
	v_mov_b32_e32 v62, v2
	v_mov_b32_e32 v63, v2
	v_mov_b32_e32 v64, v2
	v_mov_b32_e32 v65, v2
	s_branch .LBB0_492

.LBB0_502:
	s_lshl_b32 s0, s25, 13
	v_and_b32_e32 v66, 1, v152
	s_add_i32 s2, s0, 0
	v_cmp_eq_u32_e32 vcc, 0, v66
	v_lshlrev_b32_e32 v66, 10, v155
	v_lshlrev_b32_e32 v67, 1, v154
	v_add3_u32 v66, s2, v66, v67
	s_nop 0
	s_barrier
	v_readlane_b32 s25, v243, 63
	s_nop 1
	v_mov_b32_dpp v67, v50 quad_perm:[1,0,3,2] row_mask:0xf bank_mask:0xf bound_ctrl:1
	v_cvt_pk_bf16_f32 v50, v50, v67
	v_mov_b32_dpp v67, v34 quad_perm:[1,0,3,2] row_mask:0xf bank_mask:0xf bound_ctrl:1
	v_cvt_pk_bf16_f32 v34, v34, v67
	v_mov_b32_dpp v67, v18 quad_perm:[1,0,3,2] row_mask:0xf bank_mask:0xf bound_ctrl:1
	v_cvt_pk_bf16_f32 v18, v18, v67
	v_mov_b32_dpp v67, v2 quad_perm:[1,0,3,2] row_mask:0xf bank_mask:0xf bound_ctrl:1
	v_cvt_pk_bf16_f32 v2, v2, v67
	v_mov_b32_dpp v67, v51 quad_perm:[1,0,3,2] row_mask:0xf bank_mask:0xf bound_ctrl:1
	v_cvt_pk_bf16_f32 v51, v51, v67
	v_mov_b32_dpp v67, v35 quad_perm:[1,0,3,2] row_mask:0xf bank_mask:0xf bound_ctrl:1
	v_cvt_pk_bf16_f32 v35, v35, v67
	v_mov_b32_dpp v67, v19 quad_perm:[1,0,3,2] row_mask:0xf bank_mask:0xf bound_ctrl:1
	v_cvt_pk_bf16_f32 v19, v19, v67
	v_mov_b32_dpp v67, v3 quad_perm:[1,0,3,2] row_mask:0xf bank_mask:0xf bound_ctrl:1
	v_cvt_pk_bf16_f32 v3, v3, v67
	v_mov_b32_dpp v67, v52 quad_perm:[1,0,3,2] row_mask:0xf bank_mask:0xf bound_ctrl:1
	v_cvt_pk_bf16_f32 v52, v52, v67
	v_mov_b32_dpp v67, v36 quad_perm:[1,0,3,2] row_mask:0xf bank_mask:0xf bound_ctrl:1
	v_cvt_pk_bf16_f32 v36, v36, v67
	v_mov_b32_dpp v67, v20 quad_perm:[1,0,3,2] row_mask:0xf bank_mask:0xf bound_ctrl:1
	v_cvt_pk_bf16_f32 v20, v20, v67
	v_mov_b32_dpp v67, v4 quad_perm:[1,0,3,2] row_mask:0xf bank_mask:0xf bound_ctrl:1
	v_cvt_pk_bf16_f32 v4, v4, v67
	v_mov_b32_dpp v67, v53 quad_perm:[1,0,3,2] row_mask:0xf bank_mask:0xf bound_ctrl:1
	v_cvt_pk_bf16_f32 v53, v53, v67
	v_mov_b32_dpp v67, v37 quad_perm:[1,0,3,2] row_mask:0xf bank_mask:0xf bound_ctrl:1
	v_cvt_pk_bf16_f32 v37, v37, v67
	v_mov_b32_dpp v67, v21 quad_perm:[1,0,3,2] row_mask:0xf bank_mask:0xf bound_ctrl:1
	v_cvt_pk_bf16_f32 v21, v21, v67
	v_mov_b32_dpp v67, v5 quad_perm:[1,0,3,2] row_mask:0xf bank_mask:0xf bound_ctrl:1
	v_cvt_pk_bf16_f32 v5, v5, v67
	v_mov_b32_dpp v67, v54 quad_perm:[1,0,3,2] row_mask:0xf bank_mask:0xf bound_ctrl:1
	v_cvt_pk_bf16_f32 v54, v54, v67
	v_mov_b32_dpp v67, v38 quad_perm:[1,0,3,2] row_mask:0xf bank_mask:0xf bound_ctrl:1
	v_cvt_pk_bf16_f32 v38, v38, v67
	v_mov_b32_dpp v67, v22 quad_perm:[1,0,3,2] row_mask:0xf bank_mask:0xf bound_ctrl:1
	v_cvt_pk_bf16_f32 v22, v22, v67
	v_mov_b32_dpp v67, v6 quad_perm:[1,0,3,2] row_mask:0xf bank_mask:0xf bound_ctrl:1
	v_cvt_pk_bf16_f32 v6, v6, v67
	v_mov_b32_dpp v67, v55 quad_perm:[1,0,3,2] row_mask:0xf bank_mask:0xf bound_ctrl:1
	v_cvt_pk_bf16_f32 v55, v55, v67
	v_mov_b32_dpp v67, v39 quad_perm:[1,0,3,2] row_mask:0xf bank_mask:0xf bound_ctrl:1
	v_cvt_pk_bf16_f32 v39, v39, v67
	v_mov_b32_dpp v67, v23 quad_perm:[1,0,3,2] row_mask:0xf bank_mask:0xf bound_ctrl:1
	v_cvt_pk_bf16_f32 v23, v23, v67
	v_mov_b32_dpp v67, v7 quad_perm:[1,0,3,2] row_mask:0xf bank_mask:0xf bound_ctrl:1
	v_cvt_pk_bf16_f32 v7, v7, v67
	v_mov_b32_dpp v67, v56 quad_perm:[1,0,3,2] row_mask:0xf bank_mask:0xf bound_ctrl:1
	v_cvt_pk_bf16_f32 v56, v56, v67
	v_mov_b32_dpp v67, v40 quad_perm:[1,0,3,2] row_mask:0xf bank_mask:0xf bound_ctrl:1
	v_cvt_pk_bf16_f32 v40, v40, v67
	v_mov_b32_dpp v67, v24 quad_perm:[1,0,3,2] row_mask:0xf bank_mask:0xf bound_ctrl:1
	v_cvt_pk_bf16_f32 v24, v24, v67
	v_mov_b32_dpp v67, v8 quad_perm:[1,0,3,2] row_mask:0xf bank_mask:0xf bound_ctrl:1
	v_cvt_pk_bf16_f32 v8, v8, v67
	v_mov_b32_dpp v67, v57 quad_perm:[1,0,3,2] row_mask:0xf bank_mask:0xf bound_ctrl:1
	v_cvt_pk_bf16_f32 v57, v57, v67
	v_mov_b32_dpp v67, v41 quad_perm:[1,0,3,2] row_mask:0xf bank_mask:0xf bound_ctrl:1
	v_cvt_pk_bf16_f32 v41, v41, v67
	v_mov_b32_dpp v67, v25 quad_perm:[1,0,3,2] row_mask:0xf bank_mask:0xf bound_ctrl:1
	v_cvt_pk_bf16_f32 v25, v25, v67
	v_mov_b32_dpp v67, v9 quad_perm:[1,0,3,2] row_mask:0xf bank_mask:0xf bound_ctrl:1
	v_cvt_pk_bf16_f32 v9, v9, v67
	v_mov_b32_dpp v67, v58 quad_perm:[1,0,3,2] row_mask:0xf bank_mask:0xf bound_ctrl:1
	v_cvt_pk_bf16_f32 v58, v58, v67
	v_mov_b32_dpp v67, v42 quad_perm:[1,0,3,2] row_mask:0xf bank_mask:0xf bound_ctrl:1
	v_cvt_pk_bf16_f32 v42, v42, v67
	v_mov_b32_dpp v67, v26 quad_perm:[1,0,3,2] row_mask:0xf bank_mask:0xf bound_ctrl:1
	v_cvt_pk_bf16_f32 v26, v26, v67
	v_mov_b32_dpp v67, v10 quad_perm:[1,0,3,2] row_mask:0xf bank_mask:0xf bound_ctrl:1
	v_cvt_pk_bf16_f32 v10, v10, v67
	v_mov_b32_dpp v67, v59 quad_perm:[1,0,3,2] row_mask:0xf bank_mask:0xf bound_ctrl:1
	v_cvt_pk_bf16_f32 v59, v59, v67
	v_mov_b32_dpp v67, v43 quad_perm:[1,0,3,2] row_mask:0xf bank_mask:0xf bound_ctrl:1
	v_cvt_pk_bf16_f32 v43, v43, v67
	v_mov_b32_dpp v67, v27 quad_perm:[1,0,3,2] row_mask:0xf bank_mask:0xf bound_ctrl:1
	v_cvt_pk_bf16_f32 v27, v27, v67
	v_mov_b32_dpp v67, v11 quad_perm:[1,0,3,2] row_mask:0xf bank_mask:0xf bound_ctrl:1
	v_cvt_pk_bf16_f32 v11, v11, v67
	v_mov_b32_dpp v67, v60 quad_perm:[1,0,3,2] row_mask:0xf bank_mask:0xf bound_ctrl:1
	v_cvt_pk_bf16_f32 v60, v60, v67
	v_mov_b32_dpp v67, v44 quad_perm:[1,0,3,2] row_mask:0xf bank_mask:0xf bound_ctrl:1
	v_cvt_pk_bf16_f32 v44, v44, v67
	v_mov_b32_dpp v67, v28 quad_perm:[1,0,3,2] row_mask:0xf bank_mask:0xf bound_ctrl:1
	v_cvt_pk_bf16_f32 v28, v28, v67
	v_mov_b32_dpp v67, v12 quad_perm:[1,0,3,2] row_mask:0xf bank_mask:0xf bound_ctrl:1
	v_cvt_pk_bf16_f32 v12, v12, v67
	v_mov_b32_dpp v67, v61 quad_perm:[1,0,3,2] row_mask:0xf bank_mask:0xf bound_ctrl:1
	v_cvt_pk_bf16_f32 v61, v61, v67
	v_mov_b32_dpp v67, v45 quad_perm:[1,0,3,2] row_mask:0xf bank_mask:0xf bound_ctrl:1
	v_cvt_pk_bf16_f32 v45, v45, v67
	v_mov_b32_dpp v67, v29 quad_perm:[1,0,3,2] row_mask:0xf bank_mask:0xf bound_ctrl:1
	v_cvt_pk_bf16_f32 v29, v29, v67
	v_mov_b32_dpp v67, v13 quad_perm:[1,0,3,2] row_mask:0xf bank_mask:0xf bound_ctrl:1
	v_cvt_pk_bf16_f32 v13, v13, v67
	v_mov_b32_dpp v67, v62 quad_perm:[1,0,3,2] row_mask:0xf bank_mask:0xf bound_ctrl:1
	v_cvt_pk_bf16_f32 v62, v62, v67
	v_mov_b32_dpp v67, v46 quad_perm:[1,0,3,2] row_mask:0xf bank_mask:0xf bound_ctrl:1
	v_cvt_pk_bf16_f32 v46, v46, v67
	v_mov_b32_dpp v67, v30 quad_perm:[1,0,3,2] row_mask:0xf bank_mask:0xf bound_ctrl:1
	v_cvt_pk_bf16_f32 v30, v30, v67
	v_mov_b32_dpp v67, v14 quad_perm:[1,0,3,2] row_mask:0xf bank_mask:0xf bound_ctrl:1
	v_cvt_pk_bf16_f32 v14, v14, v67
	v_mov_b32_dpp v67, v63 quad_perm:[1,0,3,2] row_mask:0xf bank_mask:0xf bound_ctrl:1
	v_cvt_pk_bf16_f32 v63, v63, v67
	v_mov_b32_dpp v67, v47 quad_perm:[1,0,3,2] row_mask:0xf bank_mask:0xf bound_ctrl:1
	v_cvt_pk_bf16_f32 v47, v47, v67
	v_mov_b32_dpp v67, v31 quad_perm:[1,0,3,2] row_mask:0xf bank_mask:0xf bound_ctrl:1
	v_cvt_pk_bf16_f32 v31, v31, v67
	v_mov_b32_dpp v67, v15 quad_perm:[1,0,3,2] row_mask:0xf bank_mask:0xf bound_ctrl:1
	v_cvt_pk_bf16_f32 v15, v15, v67
	v_mov_b32_dpp v67, v64 quad_perm:[1,0,3,2] row_mask:0xf bank_mask:0xf bound_ctrl:1
	v_cvt_pk_bf16_f32 v64, v64, v67
	v_mov_b32_dpp v67, v48 quad_perm:[1,0,3,2] row_mask:0xf bank_mask:0xf bound_ctrl:1
	v_cvt_pk_bf16_f32 v48, v48, v67
	v_mov_b32_dpp v67, v32 quad_perm:[1,0,3,2] row_mask:0xf bank_mask:0xf bound_ctrl:1
	v_cvt_pk_bf16_f32 v32, v32, v67
	v_mov_b32_dpp v67, v16 quad_perm:[1,0,3,2] row_mask:0xf bank_mask:0xf bound_ctrl:1
	v_cvt_pk_bf16_f32 v16, v16, v67
	v_mov_b32_dpp v67, v65 quad_perm:[1,0,3,2] row_mask:0xf bank_mask:0xf bound_ctrl:1
	v_cvt_pk_bf16_f32 v65, v65, v67
	v_mov_b32_dpp v67, v49 quad_perm:[1,0,3,2] row_mask:0xf bank_mask:0xf bound_ctrl:1
	v_cvt_pk_bf16_f32 v49, v49, v67
	v_mov_b32_dpp v67, v33 quad_perm:[1,0,3,2] row_mask:0xf bank_mask:0xf bound_ctrl:1
	v_cvt_pk_bf16_f32 v33, v33, v67
	v_mov_b32_dpp v67, v17 quad_perm:[1,0,3,2] row_mask:0xf bank_mask:0xf bound_ctrl:1
	v_cvt_pk_bf16_f32 v17, v17, v67
	s_and_saveexec_b64 s[0:1], vcc
	ds_write_b32 v66, v50
	ds_write_b32 v66, v34 offset:64
	ds_write_b32 v66, v18 offset:128
	ds_write_b32 v66, v2 offset:192
	ds_write_b32 v66, v51 offset:256
	ds_write_b32 v66, v35 offset:320
	ds_write_b32 v66, v19 offset:384
	ds_write_b32 v66, v3 offset:448
	ds_write_b32 v66, v52 offset:512
	ds_write_b32 v66, v36 offset:576
	ds_write_b32 v66, v20 offset:640
	ds_write_b32 v66, v4 offset:704
	ds_write_b32 v66, v53 offset:768
	ds_write_b32 v66, v37 offset:832
	ds_write_b32 v66, v21 offset:896
	ds_write_b32 v66, v5 offset:960
	ds_write_b32 v66, v54 offset:2048
	ds_write_b32 v66, v38 offset:2112
	ds_write_b32 v66, v22 offset:2176
	ds_write_b32 v66, v6 offset:2240
	ds_write_b32 v66, v55 offset:2304
	ds_write_b32 v66, v39 offset:2368
	ds_write_b32 v66, v23 offset:2432
	ds_write_b32 v66, v7 offset:2496
	ds_write_b32 v66, v56 offset:2560
	ds_write_b32 v66, v40 offset:2624
	ds_write_b32 v66, v24 offset:2688
	ds_write_b32 v66, v8 offset:2752
	ds_write_b32 v66, v57 offset:2816
	ds_write_b32 v66, v41 offset:2880
	ds_write_b32 v66, v25 offset:2944
	ds_write_b32 v66, v9 offset:3008
	ds_write_b32 v66, v58 offset:4096
	ds_write_b32 v66, v42 offset:4160
	ds_write_b32 v66, v26 offset:4224
	ds_write_b32 v66, v10 offset:4288
	ds_write_b32 v66, v59 offset:4352
	ds_write_b32 v66, v43 offset:4416
	ds_write_b32 v66, v27 offset:4480
	ds_write_b32 v66, v11 offset:4544
	ds_write_b32 v66, v60 offset:4608
	ds_write_b32 v66, v44 offset:4672
	ds_write_b32 v66, v28 offset:4736
	ds_write_b32 v66, v12 offset:4800
	ds_write_b32 v66, v61 offset:4864
	ds_write_b32 v66, v45 offset:4928
	ds_write_b32 v66, v29 offset:4992
	ds_write_b32 v66, v13 offset:5056
	ds_write_b32 v66, v62 offset:6144
	ds_write_b32 v66, v46 offset:6208
	ds_write_b32 v66, v30 offset:6272
	ds_write_b32 v66, v14 offset:6336
	ds_write_b32 v66, v63 offset:6400
	ds_write_b32 v66, v47 offset:6464
	ds_write_b32 v66, v31 offset:6528
	ds_write_b32 v66, v15 offset:6592
	ds_write_b32 v66, v64 offset:6656
	ds_write_b32 v66, v48 offset:6720
	ds_write_b32 v66, v32 offset:6784
	ds_write_b32 v66, v16 offset:6848
	ds_write_b32 v66, v65 offset:6912
	ds_write_b32 v66, v49 offset:6976
	ds_write_b32 v66, v33 offset:7040
	ds_write_b32 v66, v17 offset:7104
	s_or_b64 exec, exec, s[0:1]
	s_lshl_b64 s[0:1], s[4:5], 12
	v_readlane_b32 s4, v245, 30
	v_readlane_b32 s5, v245, 31
	s_add_u32 s0, s4, s0
	v_lshlrev_b32_e32 v2, 4, v152
	s_addc_u32 s1, s5, s1
	v_and_b32_e32 v162, 0xf0, v2
	s_add_u32 s3, s0, s34
	v_lshrrev_b32_e32 v10, 4, v153
	v_add_u32_e32 v11, s2, v162
	s_addc_u32 s4, s1, s35
	s_ashr_i32 s29, s28, 31
	s_waitcnt lgkmcnt(0)
	v_lshl_add_u32 v2, v10, 8, v11
	s_lshl_b64 s[0:1], s[28:29], 12
	ds_read_b128 v[2:5], v2
	s_add_u32 s0, s3, s0
	s_addc_u32 s1, s4, s1
	v_lshl_add_u64 v[6:7], s[0:1], 0, v[162:163]
	v_lshlrev_b32_e32 v162, 12, v10
	v_lshl_add_u64 v[8:9], v[6:7], 0, v[162:163]
	s_waitcnt lgkmcnt(0)
	global_store_dwordx4 v[8:9], v[2:5], off offset:1024
	v_or_b32_e32 v8, 4, v10
	v_lshlrev_b32_e32 v162, 12, v8
	v_lshl_add_u32 v2, v8, 8, v11
	ds_read_b128 v[2:5], v2
	v_lshl_add_u64 v[8:9], v[6:7], 0, v[162:163]
	s_waitcnt lgkmcnt(0)
	global_store_dwordx4 v[8:9], v[2:5], off offset:1024
	v_or_b32_e32 v8, 8, v10
	s_nop 0
	v_lshl_add_u32 v2, v8, 8, v11
	ds_read_b128 v[2:5], v2
	v_lshlrev_b32_e32 v162, 12, v8
	v_lshl_add_u64 v[8:9], v[6:7], 0, v[162:163]
	s_waitcnt lgkmcnt(0)
	global_store_dwordx4 v[8:9], v[2:5], off offset:1024
	v_or_b32_e32 v8, 12, v10
	s_nop 0
	v_lshl_add_u32 v2, v8, 8, v11
	ds_read_b128 v[2:5], v2
	v_lshlrev_b32_e32 v162, 12, v8
	v_lshl_add_u64 v[8:9], v[6:7], 0, v[162:163]
	s_waitcnt lgkmcnt(0)
	global_store_dwordx4 v[8:9], v[2:5], off offset:1024
	v_or_b32_e32 v8, 16, v10
	s_nop 0
	v_lshl_add_u32 v2, v8, 8, v11
	ds_read_b128 v[2:5], v2
	v_lshlrev_b32_e32 v162, 12, v8
	v_lshl_add_u64 v[8:9], v[6:7], 0, v[162:163]
	s_waitcnt lgkmcnt(0)
	global_store_dwordx4 v[8:9], v[2:5], off offset:1024
	v_or_b32_e32 v8, 20, v10
	s_nop 0
	v_lshl_add_u32 v2, v8, 8, v11
	ds_read_b128 v[2:5], v2
	v_lshlrev_b32_e32 v162, 12, v8
	v_lshl_add_u64 v[8:9], v[6:7], 0, v[162:163]
	s_waitcnt lgkmcnt(0)
	global_store_dwordx4 v[8:9], v[2:5], off offset:1024
	v_or_b32_e32 v8, 24, v10
	s_nop 0
	v_lshl_add_u32 v2, v8, 8, v11
	ds_read_b128 v[2:5], v2
	v_lshlrev_b32_e32 v162, 12, v8
	v_lshl_add_u64 v[8:9], v[6:7], 0, v[162:163]
	s_waitcnt lgkmcnt(0)
	global_store_dwordx4 v[8:9], v[2:5], off offset:1024
	v_or_b32_e32 v8, 28, v10
	s_nop 0
	v_lshl_add_u32 v2, v8, 8, v11
	ds_read_b128 v[2:5], v2
	v_lshlrev_b32_e32 v162, 12, v8
	v_lshl_add_u64 v[6:7], v[6:7], 0, v[162:163]
	s_waitcnt lgkmcnt(0)
	global_store_dwordx4 v[6:7], v[2:5], off offset:1024
	s_barrier
	s_and_saveexec_b64 s[0:1], s[36:37]
	s_waitcnt vmcnt(8)
	v_mov_b32_e32 v1, v247
	s_cbranch_execnz .LBB0_479
	s_branch .LBB0_480

.LBB0_635:
	v_mov_b32_e32 v168, 0
	s_and_saveexec_b64 s[0:1], s[36:37]
	s_cbranch_execz .LBB0_639
	s_mov_b64 s[4:5], exec
	v_mbcnt_lo_u32_b32 v1, s4, 0
	v_mbcnt_hi_u32_b32 v1, s5, v1
	v_cmp_eq_u32_e32 vcc, 0, v1
	s_and_saveexec_b64 s[2:3], vcc
	s_cbranch_execz .LBB0_638
	s_bcnt1_i32_b64 s4, s[4:5]
	v_mov_b32_e32 v2, s4
	v_readlane_b32 s4, v242, 6
	v_readlane_b32 s5, v242, 7
	s_nop 4
	global_atomic_add v247, v163, v2, s[4:5] offset:2048 sc0
.LBB0_638:
	s_or_b64 exec, exec, s[2:3]
.LBB0_639:
	s_or_b64 exec, exec, s[0:1]
	s_abs_i32 s0, s13
	v_readlane_b32 s1, v243, 0
	s_mul_hi_u32 s1, s0, s1
	v_readlane_b32 s4, v243, 53
	s_mul_i32 s2, s1, s4
	s_sub_i32 s0, s0, s2
	s_ashr_i32 s8, s13, 31
	s_add_i32 s2, s1, 1
	s_sub_i32 s3, s0, s4
	s_cmp_ge_u32 s0, s4
	s_cselect_b32 s1, s2, s1
	s_cselect_b32 s0, s3, s0
	s_add_i32 s2, s1, 1
	s_cmp_ge_u32 s0, s4
	s_cselect_b32 s0, s2, s1
	s_xor_b32 s11, s0, s8
	s_sub_i32 s9, s11, s8
	s_mul_i32 s0, s9, s4
	s_sub_i32 s0, s13, s0
	v_readlane_b32 s1, v243, 54
	s_add_i32 s0, s0, s1
	s_ashr_i32 s1, s0, 31
	s_lshl_b64 s[2:3], s[0:1], 13
	v_readlane_b32 s4, v245, 11
	v_mov_b32_e32 v180, v0
	v_readlane_b32 s5, v245, 12
	s_add_u32 s2, s4, s2
	s_addc_u32 s3, s5, s3
	v_lshlrev_b32_e32 v6, 2, v180
	v_ashrrev_i32_e32 v7, 31, v6
	v_lshl_add_u64 v[2:3], v[6:7], 2, s[2:3]
	global_load_dwordx4 v[2:5], v[2:3], off
	v_and_b32_e32 v7, 64, v176
	v_add_u32_e32 v1, -1, v176
	v_cmp_lt_i32_e32 vcc, v1, v7
	v_and_b32_e32 v169, 63, v180
	v_add_u32_e32 v8, -2, v176
	v_cndmask_b32_e32 v1, v1, v176, vcc
	v_lshlrev_b32_e32 v1, 2, v1
	v_cmp_eq_u32_e32 vcc, 0, v169
	v_readfirstlane_b32 s13, v180
	s_ashr_i32 s5, s13, 6
	s_waitcnt vmcnt(0)
	v_add_f32_e32 v3, v2, v3
	v_add_f32_e32 v4, v4, v3
	v_add_f32_e32 v5, v5, v4
	ds_bpermute_b32 v1, v1, v5
	s_waitcnt lgkmcnt(0)
	v_add_f32_e32 v1, v5, v1
	v_cndmask_b32_e32 v1, v1, v5, vcc
	v_cmp_lt_i32_e32 vcc, v8, v7
	s_nop 1
	v_cndmask_b32_e32 v8, v8, v176, vcc
	v_lshlrev_b32_e32 v8, 2, v8
	ds_bpermute_b32 v8, v8, v1
	v_cmp_gt_u32_e32 vcc, 2, v169
	s_waitcnt lgkmcnt(0)
	v_add_f32_e32 v8, v1, v8
	v_cndmask_b32_e32 v1, v8, v1, vcc
	v_add_u32_e32 v8, -4, v176
	v_cmp_lt_i32_e32 vcc, v8, v7
	s_nop 1
	v_cndmask_b32_e32 v8, v8, v176, vcc
	v_lshlrev_b32_e32 v8, 2, v8
	ds_bpermute_b32 v8, v8, v1
	v_cmp_gt_u32_e32 vcc, 4, v169
	s_waitcnt lgkmcnt(0)
	v_add_f32_e32 v8, v1, v8
	v_cndmask_b32_e32 v1, v8, v1, vcc
	v_add_u32_e32 v8, -8, v176
	v_cmp_lt_i32_e32 vcc, v8, v7
	s_nop 1
	v_cndmask_b32_e32 v8, v8, v176, vcc
	v_lshlrev_b32_e32 v8, 2, v8
	ds_bpermute_b32 v8, v8, v1
	v_cmp_gt_u32_e32 vcc, 8, v169
	s_waitcnt lgkmcnt(0)
	v_add_f32_e32 v8, v1, v8
	v_cndmask_b32_e32 v1, v8, v1, vcc
	v_add_u32_e32 v8, -16, v176
	v_cmp_lt_i32_e32 vcc, v8, v7
	s_nop 1
	v_cndmask_b32_e32 v8, v8, v176, vcc
	v_lshlrev_b32_e32 v8, 2, v8
	ds_bpermute_b32 v8, v8, v1
	v_cmp_gt_u32_e32 vcc, 16, v169
	s_waitcnt lgkmcnt(0)
	v_add_f32_e32 v8, v1, v8
	v_cndmask_b32_e32 v1, v8, v1, vcc
	v_subrev_u32_e32 v8, 32, v176
	v_cmp_lt_i32_e32 vcc, v8, v7
	s_nop 1
	v_cndmask_b32_e32 v7, v8, v176, vcc
	v_lshlrev_b32_e32 v7, 2, v7
	ds_bpermute_b32 v7, v7, v1
	v_cmp_eq_u32_e32 vcc, 63, v169
	s_waitcnt lgkmcnt(0)
	v_add_f32_e32 v7, v1, v7
	s_and_saveexec_b64 s[2:3], vcc
	s_lshl_b32 s1, s5, 2
	s_add_i32 s1, s1, 0
	s_add_i32 s1, s1, 0x12840
	v_mov_b32_e32 v8, s1
	ds_write_b32 v8, v7
	s_or_b64 exec, exec, s[2:3]
	s_mul_hi_i32 s1, s0, 0x2aaaaaab
	s_lshr_b32 s2, s1, 31
	s_add_i32 s18, s1, s2
	s_lshl_b32 s2, s9, 8
	s_mul_i32 s1, s18, 6
	s_ashr_i32 s19, s18, 31
	s_sub_i32 s2, 0x700, s2
	s_sub_i32 s3, s0, s1
	s_lshl_b64 s[0:1], s[18:19], 11
	s_ashr_i32 s4, s2, 31
	s_add_u32 s96, s0, s2
	s_addc_u32 s97, s1, s4
	s_mul_i32 s0, s97, 0x3000
	s_mul_hi_u32 s1, s96, 0x3000
	s_add_i32 s1, s1, s0
	s_mul_i32 s0, s96, 0x3000
	v_readlane_b32 s20, v245, 14
	s_add_u32 s4, s20, s0
	v_readlane_b32 s21, v245, 15
	s_addc_u32 s19, s21, s1
	s_lshl_b32 s0, s3, 7
	s_ashr_i32 s1, s0, 31
	s_lshl_b64 s[34:35], s[0:1], 1
	s_add_u32 s0, s4, s34
	s_addc_u32 s1, s19, s35
	s_add_u32 s0, s0, 0x1e00
	s_addc_u32 s1, s1, 0
	s_mul_i32 s4, s18, 0x1800000
	s_mul_hi_i32 s3, s18, 0x1800000
	s_add_u32 s4, s20, s4
	s_addc_u32 s3, s21, s3
	s_add_u32 s4, s4, s34
	s_addc_u32 s3, s3, s35
	s_add_u32 s22, s4, 0x2400
	s_addc_u32 s23, s3, 0
	s_add_u32 s28, s4, 0x2a00
	s_addc_u32 s29, s3, 0
	v_lshlrev_b32_e32 v22, 3, v180
	v_cmp_gt_u32_e64 s[38:39], 32, v169
	s_add_i32 s3, 0, 0x12840
	v_and_b32_e32 v8, 0x78, v22
	v_cndmask_b32_e64 v1, v7, v1, s[38:39]
	v_mov_b32_e32 v7, s3
	v_lshlrev_b32_e32 v50, 1, v8
	s_waitcnt lgkmcnt(0)
	s_barrier
	ds_read_b128 v[8:11], v7
	s_ashr_i32 s3, s2, 8
	v_readlane_b32 s4, v243, 56
	s_cmp_gt_i32 s5, 0
	s_cselect_b64 vcc, -1, 0
	v_mov_b32_e32 v7, s4
	ds_read_b128 v[12:15], v7
	s_waitcnt lgkmcnt(1)
	v_add_f32_e32 v7, 0, v8
	s_cmp_gt_i32 s3, -1
	v_cndmask_b32_e32 v8, 0, v7, vcc
	s_cselect_b64 vcc, -1, 0
	s_cmp_gt_i32 s5, 1
	v_cndmask_b32_e32 v7, 0, v7, vcc
	v_add_f32_e32 v16, v9, v8
	s_cselect_b64 vcc, -1, 0
	s_cmp_lt_i32 s3, 1
	v_cndmask_b32_e32 v8, v8, v16, vcc
	v_add_f32_e32 v9, v9, v7
	s_cselect_b64 vcc, -1, 0
	s_cmp_gt_i32 s5, 2
	v_cndmask_b32_e32 v7, v9, v7, vcc
	v_add_f32_e32 v9, v10, v8
	s_cselect_b64 vcc, -1, 0
	s_cmp_lt_i32 s3, 2
	v_cndmask_b32_e32 v8, v8, v9, vcc
	v_add_f32_e32 v9, v10, v7
	s_cselect_b64 vcc, -1, 0
	s_cmp_gt_i32 s5, 3
	v_cndmask_b32_e32 v7, v9, v7, vcc
	v_add_f32_e32 v9, v11, v8
	s_cselect_b64 vcc, -1, 0
	s_cmp_lt_i32 s3, 3
	v_cndmask_b32_e32 v8, v8, v9, vcc
	v_add_f32_e32 v9, v11, v7
	s_cselect_b64 vcc, -1, 0
	s_cmp_gt_i32 s5, 4
	v_cndmask_b32_e32 v7, v9, v7, vcc
	s_waitcnt lgkmcnt(0)
	v_add_f32_e32 v9, v12, v8
	s_cselect_b64 vcc, -1, 0
	s_cmp_lt_i32 s3, 4
	v_cndmask_b32_e32 v8, v8, v9, vcc
	v_add_f32_e32 v9, v12, v7
	s_cselect_b64 vcc, -1, 0
	s_cmp_gt_i32 s5, 5
	v_cndmask_b32_e32 v7, v9, v7, vcc
	v_add_f32_e32 v9, v13, v8
	s_cselect_b64 vcc, -1, 0
	s_cmp_lt_i32 s3, 5
	v_cndmask_b32_e32 v8, v8, v9, vcc
	v_add_f32_e32 v9, v13, v7
	s_cselect_b64 vcc, -1, 0
	s_cmp_gt_i32 s5, 6
	v_cndmask_b32_e32 v7, v9, v7, vcc
	v_add_f32_e32 v9, v14, v8
	s_cselect_b64 vcc, -1, 0
	s_cmp_lt_i32 s3, 6
	v_cndmask_b32_e32 v8, v8, v9, vcc
	v_add_f32_e32 v9, v14, v7
	s_cselect_b64 vcc, -1, 0
	s_cmp_gt_i32 s5, 7
	v_cndmask_b32_e32 v7, v9, v7, vcc
	v_add_f32_e32 v9, v15, v8
	s_cselect_b64 vcc, -1, 0
	s_cmp_lt_i32 s3, 7
	v_cndmask_b32_e32 v8, v8, v9, vcc
	v_add_f32_e32 v9, v15, v7
	s_cselect_b64 vcc, -1, 0
	v_sub_f32_e32 v1, v1, v5
	v_cndmask_b32_e32 v7, v9, v7, vcc
	v_add_f32_e32 v1, v1, v8
	v_sub_f32_e32 v8, v1, v7
	v_ashrrev_i32_e32 v192, 4, v180
	v_add_f32 v2, v2, v8
	v_add_f32 v3, v3, v8
	v_add_f32 v4, v4, v8
	v_add_f32 v5, v5, v8
	s_mov_b32 s4, 0x3fb8aa3b
	v_readlane_b32 s3, v243, 57
	v_add_u32_e32 v23, 32, v192
	v_mul_f32 v4, v4, s4
	v_mul_f32 v5, v5, s4
	v_mul_f32 v2, v2, s4
	v_mul_f32 v3, v3, s4
	v_lshl_add_u32 v1, v6, 2, s3
	v_mov_b64_e32 v[18:19], s[28:29]
	v_mov_b64_e32 v[20:21], s[22:23]
	ds_write_b128 v1, v[2:5]
	v_mad_i64_i32 v[2:3], s[18:19], v192, s33, v[18:19]
	v_mov_b32_e32 v51, v163
	v_mad_i64_i32 v[6:7], s[18:19], v192, s33, v[20:21]
	v_mad_i64_i32 v[8:9], s[18:19], v23, s33, v[20:21]
	v_lshl_add_u64 v[2:3], v[2:3], 0, v[50:51]
	v_lshl_add_u64 v[6:7], v[6:7], 0, v[50:51]
	v_lshl_add_u64 v[10:11], v[8:9], 0, v[50:51]
	s_waitcnt lgkmcnt(0)
	s_barrier
	global_load_dwordx4 v[2:5], v[2:3], off
	s_nop 0
	global_load_dwordx4 v[6:9], v[6:7], off
	s_nop 0
	global_load_dwordx4 v[10:13], v[10:11], off
	v_mad_i64_i32 v[14:15], s[18:19], v23, s33, v[18:19]
	v_lshl_add_u64 v[14:15], v[14:15], 0, v[50:51]
	global_load_dwordx4 v[14:17], v[14:15], off
	v_and_b32_e32 v1, 0xfffff0, v192
	v_lshlrev_b32_e32 v24, 1, v192
	v_and_or_b32 v1, v24, 8, v1
	v_lshrrev_b32_e32 v24, 1, v192
	v_and_b32_e32 v25, 3, v192
	v_and_or_b32 v24, v24, 4, v25
	v_and_b32_e32 v25, 0xfffff0, v23
	v_lshlrev_b32_e32 v23, 1, v23
	v_and_or_b32 v23, v23, 8, v25
	v_lshrrev_b32_e32 v1, 1, v1
	v_bfe_u32 v22, v22, 5, 2
	v_lshrrev_b32_e32 v23, 1, v23
	v_or_b32_e32 v1, v1, v22
	v_or_b32_e32 v22, v23, v22
	v_lshlrev_b32_e32 v23, 8, v192
	v_and_b32_e32 v25, 0x70, v180
	v_lshlrev_b32_e32 v1, 9, v1
	v_lshlrev_b32_e32 v24, 6, v24
	v_lshlrev_b32_e32 v22, 9, v22
	v_bitop3_b32 v25, v50, v23, v25 bitop3:0xde
	v_and_b32_e32 v182, 31, v180
	v_and_b32_e32 v23, 48, v50
	s_lshl_b32 s4, s5, 5
	v_lshrrev_b32_e32 v181, 5, v169
	v_or3_b32 v1, v1, v24, v23
	v_or3_b32 v24, v22, v24, v23
	v_or_b32_e32 v26, s4, v182
	v_mov_b64_e32 v[22:23], s[0:1]
	v_mad_i64_i32 v[22:23], s[0:1], v26, s33, v[22:23]
	v_lshlrev_b32_e32 v162, 4, v181
	v_lshl_add_u64 v[22:23], v[22:23], 0, v[162:163]
	global_load_dwordx4 v[142:145], v[22:23], off
	global_load_dwordx4 v[138:141], v[22:23], off offset:32
	global_load_dwordx4 v[134:137], v[22:23], off offset:64
	global_load_dwordx4 v[130:133], v[22:23], off offset:96
	global_load_dwordx4 v[126:129], v[22:23], off offset:128
	global_load_dwordx4 v[122:125], v[22:23], off offset:160
	global_load_dwordx4 v[118:121], v[22:23], off offset:192
	global_load_dwordx4 v[114:117], v[22:23], off offset:224
	v_add_u32_e32 v193, 0, v25
	v_add_u32_e32 v194, 0, v1
	v_add_u32_e32 v1, 64, v192
	s_waitcnt vmcnt(10)
	ds_write_b128 v193, v[6:9] offset:32768
	s_waitcnt vmcnt(9)
	ds_write_b128 v193, v[10:13] offset:40960
	ds_write_b128 v194, v[2:5]
	v_mad_i64_i32 v[2:3], s[0:1], v1, s33, v[18:19]
	v_add_u32_e32 v6, 0x60, v192
	v_add_u32_e32 v195, 0, v24
	v_lshl_add_u64 v[2:3], v[2:3], 0, v[50:51]
	v_mad_i64_i32 v[4:5], s[0:1], v6, s33, v[18:19]
	s_waitcnt vmcnt(8)
	ds_write_b128 v195, v[14:17]
	s_waitcnt lgkmcnt(0)
	s_barrier
	v_lshl_add_u64 v[4:5], v[4:5], 0, v[50:51]
	global_load_dwordx4 v[38:41], v[2:3], off
	global_load_dwordx4 v[34:37], v[4:5], off
	v_mad_i64_i32 v[2:3], s[0:1], v1, s33, v[20:21]
	v_lshl_add_u64 v[2:3], v[2:3], 0, v[50:51]
	v_mad_i64_i32 v[4:5], s[0:1], v6, s33, v[20:21]
	v_lshl_add_u64 v[4:5], v[4:5], 0, v[50:51]
	global_load_dwordx4 v[46:49], v[2:3], off
	global_load_dwordx4 v[42:45], v[4:5], off
	v_lshlrev_b32_e32 v186, 2, v181
	v_sub_u32_e32 v1, v182, v186
	v_lshlrev_b32_e32 v179, 4, v180
	s_movk_i32 s0, 0x70
	v_and_b32_e32 v2, 0x70, v179
	v_lshl_add_u32 v3, v182, 8, 0
	v_bitop3_b32 v4, v162, v179, s0 bitop3:0x78
	v_add_u32_e32 v191, v3, v4
	v_bitop3_b32 v4, v162, v2, 32 bitop3:0x36
	s_movk_i32 s0, 0x60
	v_add_u32_e32 v190, v3, v4
	v_bitop3_b32 v4, v162, v2, 64 bitop3:0x36
	v_bitop3_b32 v2, v162, v2, s0 bitop3:0x36
	v_add_u32_e32 v189, v3, v4
	v_add_u32_e32 v188, v3, v2
	ds_read_b128 v[2:5], v191 offset:32768
	ds_read_b128 v[6:9], v191 offset:40960
	s_waitcnt vmcnt(11) lgkmcnt(1)
	v_mfma_f32_32x32x16_bf16 v[18:33], v[2:5], v[142:145], 0
	ds_read_b128 v[52:55], v190 offset:32768
	ds_read_b128 v[56:59], v190 offset:40960
	v_add_u32_e32 v51, s3, v162
	s_add_i32 s27, s4, s2
	v_add_u32_e32 v187, s27, v1
	s_cmp_gt_i32 s27, 62
	s_waitcnt lgkmcnt(2)
	v_mfma_f32_32x32x16_bf16 v[2:17], v[6:9], v[142:145], 0
	s_waitcnt vmcnt(10) lgkmcnt(1)
	v_mfma_f32_32x32x16_bf16 v[18:33], v[52:55], v[138:141], v[18:33]
	s_waitcnt lgkmcnt(0)
	v_mfma_f32_32x32x16_bf16 v[2:17], v[56:59], v[138:141], v[2:17]
	ds_read_b128 v[52:55], v189 offset:32768
	ds_read_b128 v[56:59], v189 offset:40960
	s_waitcnt vmcnt(9) lgkmcnt(1)
	v_mfma_f32_32x32x16_bf16 v[18:33], v[52:55], v[134:137], v[18:33]
	s_waitcnt lgkmcnt(0)
	v_mfma_f32_32x32x16_bf16 v[2:17], v[56:59], v[134:137], v[2:17]
	ds_read_b128 v[52:55], v188 offset:32768
	ds_read_b128 v[56:59], v188 offset:40960
	s_waitcnt vmcnt(8) lgkmcnt(1)
	v_mfma_f32_32x32x16_bf16 v[18:33], v[52:55], v[130:133], v[18:33]
	s_waitcnt lgkmcnt(0)
	v_mfma_f32_32x32x16_bf16 v[2:17], v[56:59], v[130:133], v[2:17]
	ds_read_b128 v[52:55], v191 offset:32896
	ds_read_b128 v[56:59], v191 offset:41088
	s_waitcnt vmcnt(7) lgkmcnt(1)
	v_mfma_f32_32x32x16_bf16 v[18:33], v[52:55], v[126:129], v[18:33]
	s_waitcnt lgkmcnt(0)
	v_mfma_f32_32x32x16_bf16 v[2:17], v[56:59], v[126:129], v[2:17]
	ds_read_b128 v[52:55], v190 offset:32896
	ds_read_b128 v[56:59], v190 offset:41088
	s_waitcnt vmcnt(6) lgkmcnt(1)
	v_mfma_f32_32x32x16_bf16 v[18:33], v[52:55], v[122:125], v[18:33]
	s_waitcnt lgkmcnt(0)
	v_mfma_f32_32x32x16_bf16 v[2:17], v[56:59], v[122:125], v[2:17]
	ds_read_b128 v[52:55], v189 offset:32896
	ds_read_b128 v[56:59], v189 offset:41088
	s_waitcnt vmcnt(5) lgkmcnt(1)
	v_mfma_f32_32x32x16_bf16 v[18:33], v[52:55], v[118:121], v[18:33]
	s_waitcnt lgkmcnt(0)
	v_mfma_f32_32x32x16_bf16 v[2:17], v[56:59], v[118:121], v[2:17]
	ds_read_b128 v[52:55], v188 offset:32896
	ds_read_b128 v[56:59], v188 offset:41088
	s_waitcnt vmcnt(4) lgkmcnt(1)
	v_mfma_f32_32x32x16_bf16 v[18:33], v[52:55], v[114:117], v[18:33]
	v_add_u32_e32 v52, 0, v162
	v_add_u32_e32 v80, 0x10880, v52
	s_waitcnt lgkmcnt(0)
	v_mfma_f32_32x32x16_bf16 v[2:17], v[56:59], v[114:117], v[2:17]
	ds_read_b128 v[52:55], v51
	ds_read_b128 v[56:59], v51 offset:32
	ds_read_b128 v[60:63], v80
	ds_read_b128 v[64:67], v80 offset:32
	ds_read_b128 v[68:71], v51 offset:64
	ds_read_b128 v[72:75], v80 offset:64
	ds_read_b128 v[76:79], v51 offset:96
	ds_read_b128 v[80:83], v80 offset:96
	s_waitcnt lgkmcnt(7)
	s_waitcnt lgkmcnt(6)
	s_waitcnt lgkmcnt(3)
	v_xor_b32_e32 v71, 0x80000000, v71
	v_xor_b32_e32 v70, 0x80000000, v70
	s_waitcnt lgkmcnt(1)
	v_xor_b32_e32 v79, 0x80000000, v79
	v_xor_b32_e32 v78, 0x80000000, v78
	v_fma_f32 v24, v24, s12, -v58
	v_fma_f32 v25, v25, s12, -v59
	v_fma_f32 v22, v22, s12, -v56
	v_fma_f32 v23, v23, s12, -v57
	v_fma_f32 v20, v20, s12, -v54
	v_fma_f32 v21, v21, s12, -v55
	v_fma_f32 v18, v18, s12, -v52
	v_fma_f32 v19, v19, s12, -v53
	v_xor_b32_e32 v53, 0x80000000, v63
	v_xor_b32_e32 v52, 0x80000000, v62
	v_xor_b32_e32 v55, 0x80000000, v67
	v_xor_b32_e32 v54, 0x80000000, v66
	v_xor_b32_e32 v57, 0x80000000, v75
	v_xor_b32_e32 v56, 0x80000000, v74
	s_waitcnt lgkmcnt(0)
	v_xor_b32_e32 v59, 0x80000000, v83
	v_xor_b32_e32 v58, 0x80000000, v82
	v_fma_f32 v32, v32, s12, v78
	v_fma_f32 v33, v33, s12, v79
	v_fma_f32 v30, v30, s12, -v76
	v_fma_f32 v31, v31, s12, -v77
	v_fma_f32 v28, v28, s12, v70
	v_fma_f32 v29, v29, s12, v71
	v_fma_f32 v26, v26, s12, -v68
	v_fma_f32 v27, v27, s12, -v69
	v_fma_f32 v16, v16, s12, v58
	v_fma_f32 v17, v17, s12, v59
	v_fma_f32 v14, v14, s12, -v80
	v_fma_f32 v15, v15, s12, -v81
	v_fma_f32 v12, v12, s12, v56
	v_fma_f32 v13, v13, s12, v57
	v_fma_f32 v10, v10, s12, -v72
	v_fma_f32 v11, v11, s12, -v73
	v_fma_f32 v8, v8, s12, v54
	v_fma_f32 v9, v9, s12, v55
	v_fma_f32 v6, v6, s12, -v64
	v_fma_f32 v7, v7, s12, -v65
	v_fma_f32 v4, v4, s12, v52
	v_fma_f32 v5, v5, s12, v53
	v_fma_f32 v2, v2, s12, -v60
	v_fma_f32 v3, v3, s12, -v61
	s_cbranch_scc1 .LBB0_643
	v_cmp_gt_i32_e64 s[92:93], 26, v187
	v_cmp_gt_i32_e64 s[94:95], 27, v187
	v_cmp_gt_i32_e64 s[90:91], 25, v187
	s_and_b64 s[92:93], s[94:95], s[92:93]
	v_cmp_gt_i32_e64 s[88:89], 24, v187
	s_and_b64 s[90:91], s[92:93], s[90:91]
	v_cmp_gt_i32_e64 s[86:87], 19, v187
	s_and_b64 s[88:89], s[90:91], s[88:89]
	v_cmp_gt_i32_e64 s[84:85], 18, v187
	s_and_b64 s[86:87], s[88:89], s[86:87]
	v_cmp_gt_i32_e64 s[82:83], 17, v187
	s_and_b64 s[84:85], s[86:87], s[84:85]
	v_cmp_gt_i32_e64 s[80:81], 16, v187
	s_and_b64 s[82:83], s[84:85], s[82:83]
	v_cmp_gt_i32_e64 s[78:79], 11, v187
	s_and_b64 s[80:81], s[82:83], s[80:81]
	v_cmp_gt_i32_e64 s[76:77], 10, v187
	s_and_b64 s[78:79], s[80:81], s[78:79]
	v_cmp_gt_i32_e64 s[74:75], 9, v187
	s_and_b64 s[76:77], s[78:79], s[76:77]
	v_cmp_gt_i32_e64 s[72:73], 8, v187
	s_and_b64 s[74:75], s[76:77], s[74:75]
	v_cmp_gt_i32_e64 s[70:71], 3, v187
	s_and_b64 s[72:73], s[74:75], s[72:73]
	v_cmp_gt_i32_e64 s[68:69], 2, v187
	s_and_b64 s[70:71], s[72:73], s[70:71]
	v_cmp_gt_i32_e64 s[2:3], 1, v187
	s_and_b64 s[68:69], s[70:71], s[68:69]
	v_cmp_gt_i32_e64 s[0:1], 0, v187
	s_and_b64 s[2:3], s[68:69], s[2:3]
	s_and_b64 s[0:1], s[2:3], s[0:1]
	v_cmp_gt_i32_e64 s[66:67], 58, v187
	v_cndmask_b32_e64 v18, v18, v175, s[0:1]
	v_cmp_gt_i32_e64 s[0:1], 59, v187
	v_cmp_gt_i32_e64 s[64:65], 57, v187
	v_cmp_gt_i32_e64 s[62:63], 56, v187
	v_cndmask_b32_e64 v17, v17, v175, s[0:1]
	s_and_b64 s[0:1], s[0:1], s[66:67]
	v_cndmask_b32_e64 v16, v16, v175, s[0:1]
	s_and_b64 s[0:1], s[0:1], s[64:65]
	v_cmp_gt_i32_e64 s[60:61], 51, v187
	v_cndmask_b32_e64 v15, v15, v175, s[0:1]
	s_and_b64 s[0:1], s[0:1], s[62:63]
	v_cmp_gt_i32_e64 s[58:59], 50, v187
	v_cndmask_b32_e64 v14, v14, v175, s[0:1]
	s_and_b64 s[0:1], s[0:1], s[60:61]
	v_cmp_gt_i32_e64 s[56:57], 49, v187
	v_cndmask_b32_e64 v13, v13, v175, s[0:1]
	s_and_b64 s[0:1], s[0:1], s[58:59]
	v_cmp_gt_i32_e64 s[54:55], 48, v187
	v_cndmask_b32_e64 v12, v12, v175, s[0:1]
	s_and_b64 s[0:1], s[0:1], s[56:57]
	v_cmp_gt_i32_e64 s[52:53], 43, v187
	v_cndmask_b32_e64 v11, v11, v175, s[0:1]
	s_and_b64 s[0:1], s[0:1], s[54:55]
	v_cmp_gt_i32_e64 s[50:51], 42, v187
	v_cndmask_b32_e64 v10, v10, v175, s[0:1]
	s_and_b64 s[0:1], s[0:1], s[52:53]
	v_cmp_gt_i32_e64 s[48:49], 41, v187
	v_cndmask_b32_e64 v9, v9, v175, s[0:1]
	s_and_b64 s[0:1], s[0:1], s[50:51]
	v_cmp_gt_i32_e64 s[46:47], 40, v187
	v_cndmask_b32_e64 v8, v8, v175, s[0:1]
	s_and_b64 s[0:1], s[0:1], s[48:49]
	v_cmp_gt_i32_e64 s[44:45], 35, v187
	v_cndmask_b32_e64 v7, v7, v175, s[0:1]
	s_and_b64 s[0:1], s[0:1], s[46:47]
	v_cmp_gt_i32_e64 s[42:43], 34, v187
	v_cndmask_b32_e64 v6, v6, v175, s[0:1]
	s_and_b64 s[0:1], s[0:1], s[44:45]
	v_cmp_gt_i32_e64 s[40:41], 33, v187
	v_cndmask_b32_e64 v5, v5, v175, s[0:1]
	s_and_b64 s[0:1], s[0:1], s[42:43]
	v_cmp_gt_i32_e32 vcc, 32, v187
	v_cndmask_b32_e64 v4, v4, v175, s[0:1]
	s_and_b64 s[0:1], s[0:1], s[40:41]
	v_cndmask_b32_e64 v30, v30, v175, s[88:89]
	v_readlane_b32 s88, v242, 2
	s_and_b64 vcc, s[0:1], vcc
	v_cndmask_b32_e64 v33, v33, v175, s[94:95]
	v_cndmask_b32_e64 v32, v32, v175, s[92:93]
	s_movk_i32 s93, 0x6018
	s_mov_b32 s92, 0xf800000
	v_cndmask_b32_e64 v31, v31, v175, s[90:91]
	s_mov_b64 s[90:91], s[16:17]
	v_readlane_b32 s89, v242, 3
	v_cndmask_b32_e64 v29, v29, v175, s[86:87]
	v_readlane_b32 s86, v242, 0
	v_cndmask_b32_e64 v28, v28, v175, s[84:85]
	v_cndmask_b32_e64 v27, v27, v175, s[82:83]
	s_movk_i32 s83, 0x6000
	v_cndmask_b32_e64 v26, v26, v175, s[80:81]
	v_cndmask_b32_e64 v25, v25, v175, s[78:79]
	v_cndmask_b32_e64 v24, v24, v175, s[76:77]
	v_cndmask_b32_e64 v23, v23, v175, s[74:75]
	v_cndmask_b32_e64 v22, v22, v175, s[72:73]
	v_cndmask_b32_e64 v21, v21, v175, s[70:71]
	v_cndmask_b32_e64 v20, v20, v175, s[68:69]
	v_cndmask_b32_e64 v19, v19, v175, s[2:3]
	s_mov_b32 s56, s30
	v_cndmask_b32_e64 v3, v3, v175, s[0:1]
	v_cndmask_b32_e32 v2, v2, v175, vcc
	v_readlane_b32 s87, v242, 1

.Lmskip_fox_6:
	s_and_saveexec_b64 s[0:1], s[38:39]
	v_add_f32_e32 v1, v1, v114
	v_fmac_f32_e32 v1, v162, v146
	v_add_f32_e32 v66, v66, v67
	v_fmac_f32_e32 v66, v1, v96
	ds_write_b32 v185, v66
	s_or_b64 exec, exec, s[0:1]
	s_waitcnt lgkmcnt(0)
	ds_read_b128 v[78:81], v184
	ds_read_b128 v[74:77], v184 offset:32
	ds_read_b128 v[70:73], v184 offset:64
	ds_read_b128 v[66:69], v184 offset:96
	s_lshl_b32 s0, s5, 13
	s_waitcnt lgkmcnt(3)
	v_and_b32_e32 v1, 1, v180
	s_add_i32 s2, s0, 0
	v_cmp_eq_u32_e32 vcc, 0, v1
	v_lshlrev_b32_e32 v1, 10, v181
	v_lshlrev_b32_e32 v82, 1, v182
	v_add3_u32 v1, s2, v1, v82
	s_waitcnt lgkmcnt(0)
	s_barrier
	v_rcp_f32_e32 v66, v66
	v_rcp_f32_e32 v67, v67
	v_rcp_f32_e32 v68, v68
	v_rcp_f32_e32 v69, v69
	v_rcp_f32_e32 v70, v70
	v_rcp_f32_e32 v71, v71
	v_rcp_f32_e32 v72, v72
	v_rcp_f32_e32 v73, v73
	v_rcp_f32_e32 v74, v74
	v_rcp_f32_e32 v75, v75
	v_rcp_f32_e32 v76, v76
	v_rcp_f32_e32 v77, v77
	v_rcp_f32_e32 v78, v78
	v_rcp_f32_e32 v79, v79
	v_rcp_f32_e32 v80, v80
	v_rcp_f32_e32 v81, v81
	s_nop 1
	v_mul_f32_dpp v82, v50, v78 quad_perm:[1,0,3,2] row_mask:0xf bank_mask:0xf bound_ctrl:1
	v_mul_f32_e32 v50, v50, v78
	v_cvt_pk_bf16_f32 v50, v50, v82
	v_mul_f32_dpp v82, v34, v78 quad_perm:[1,0,3,2] row_mask:0xf bank_mask:0xf bound_ctrl:1
	v_mul_f32_e32 v34, v34, v78
	v_cvt_pk_bf16_f32 v34, v34, v82
	v_mul_f32_dpp v82, v18, v78 quad_perm:[1,0,3,2] row_mask:0xf bank_mask:0xf bound_ctrl:1
	v_mul_f32_e32 v18, v18, v78
	v_cvt_pk_bf16_f32 v18, v18, v82
	v_mul_f32_dpp v82, v2, v78 quad_perm:[1,0,3,2] row_mask:0xf bank_mask:0xf bound_ctrl:1
	v_mul_f32_e32 v2, v2, v78
	v_cvt_pk_bf16_f32 v2, v2, v82
	v_mul_f32_dpp v82, v51, v79 quad_perm:[1,0,3,2] row_mask:0xf bank_mask:0xf bound_ctrl:1
	v_mul_f32_e32 v51, v51, v79
	v_cvt_pk_bf16_f32 v51, v51, v82
	v_mul_f32_dpp v82, v35, v79 quad_perm:[1,0,3,2] row_mask:0xf bank_mask:0xf bound_ctrl:1
	v_mul_f32_e32 v35, v35, v79
	v_cvt_pk_bf16_f32 v35, v35, v82
	v_mul_f32_dpp v82, v19, v79 quad_perm:[1,0,3,2] row_mask:0xf bank_mask:0xf bound_ctrl:1
	v_mul_f32_e32 v19, v19, v79
	v_cvt_pk_bf16_f32 v19, v19, v82
	v_mul_f32_dpp v82, v3, v79 quad_perm:[1,0,3,2] row_mask:0xf bank_mask:0xf bound_ctrl:1
	v_mul_f32_e32 v3, v3, v79
	v_cvt_pk_bf16_f32 v3, v3, v82
	v_mul_f32_dpp v82, v52, v80 quad_perm:[1,0,3,2] row_mask:0xf bank_mask:0xf bound_ctrl:1
	v_mul_f32_e32 v52, v52, v80
	v_cvt_pk_bf16_f32 v52, v52, v82
	v_mul_f32_dpp v82, v36, v80 quad_perm:[1,0,3,2] row_mask:0xf bank_mask:0xf bound_ctrl:1
	v_mul_f32_e32 v36, v36, v80
	v_cvt_pk_bf16_f32 v36, v36, v82
	v_mul_f32_dpp v82, v20, v80 quad_perm:[1,0,3,2] row_mask:0xf bank_mask:0xf bound_ctrl:1
	v_mul_f32_e32 v20, v20, v80
	v_cvt_pk_bf16_f32 v20, v20, v82
	v_mul_f32_dpp v82, v4, v80 quad_perm:[1,0,3,2] row_mask:0xf bank_mask:0xf bound_ctrl:1
	v_mul_f32_e32 v4, v4, v80
	v_cvt_pk_bf16_f32 v4, v4, v82
	v_mul_f32_dpp v82, v53, v81 quad_perm:[1,0,3,2] row_mask:0xf bank_mask:0xf bound_ctrl:1
	v_mul_f32_e32 v53, v53, v81
	v_cvt_pk_bf16_f32 v53, v53, v82
	v_mul_f32_dpp v82, v37, v81 quad_perm:[1,0,3,2] row_mask:0xf bank_mask:0xf bound_ctrl:1
	v_mul_f32_e32 v37, v37, v81
	v_cvt_pk_bf16_f32 v37, v37, v82
	v_mul_f32_dpp v82, v21, v81 quad_perm:[1,0,3,2] row_mask:0xf bank_mask:0xf bound_ctrl:1
	v_mul_f32_e32 v21, v21, v81
	v_cvt_pk_bf16_f32 v21, v21, v82
	v_mul_f32_dpp v82, v5, v81 quad_perm:[1,0,3,2] row_mask:0xf bank_mask:0xf bound_ctrl:1
	v_mul_f32_e32 v5, v5, v81
	v_cvt_pk_bf16_f32 v5, v5, v82
	v_mul_f32_dpp v82, v54, v74 quad_perm:[1,0,3,2] row_mask:0xf bank_mask:0xf bound_ctrl:1
	v_mul_f32_e32 v54, v54, v74
	v_cvt_pk_bf16_f32 v54, v54, v82
	v_mul_f32_dpp v82, v38, v74 quad_perm:[1,0,3,2] row_mask:0xf bank_mask:0xf bound_ctrl:1
	v_mul_f32_e32 v38, v38, v74
	v_cvt_pk_bf16_f32 v38, v38, v82
	v_mul_f32_dpp v82, v22, v74 quad_perm:[1,0,3,2] row_mask:0xf bank_mask:0xf bound_ctrl:1
	v_mul_f32_e32 v22, v22, v74
	v_cvt_pk_bf16_f32 v22, v22, v82
	v_mul_f32_dpp v82, v6, v74 quad_perm:[1,0,3,2] row_mask:0xf bank_mask:0xf bound_ctrl:1
	v_mul_f32_e32 v6, v6, v74
	v_cvt_pk_bf16_f32 v6, v6, v82
	v_mul_f32_dpp v82, v55, v75 quad_perm:[1,0,3,2] row_mask:0xf bank_mask:0xf bound_ctrl:1
	v_mul_f32_e32 v55, v55, v75
	v_cvt_pk_bf16_f32 v55, v55, v82
	v_mul_f32_dpp v82, v39, v75 quad_perm:[1,0,3,2] row_mask:0xf bank_mask:0xf bound_ctrl:1
	v_mul_f32_e32 v39, v39, v75
	v_cvt_pk_bf16_f32 v39, v39, v82
	v_mul_f32_dpp v82, v23, v75 quad_perm:[1,0,3,2] row_mask:0xf bank_mask:0xf bound_ctrl:1
	v_mul_f32_e32 v23, v23, v75
	v_cvt_pk_bf16_f32 v23, v23, v82
	v_mul_f32_dpp v82, v7, v75 quad_perm:[1,0,3,2] row_mask:0xf bank_mask:0xf bound_ctrl:1
	v_mul_f32_e32 v7, v7, v75
	v_cvt_pk_bf16_f32 v7, v7, v82
	v_mul_f32_dpp v82, v56, v76 quad_perm:[1,0,3,2] row_mask:0xf bank_mask:0xf bound_ctrl:1
	v_mul_f32_e32 v56, v56, v76
	v_cvt_pk_bf16_f32 v56, v56, v82
	v_mul_f32_dpp v82, v40, v76 quad_perm:[1,0,3,2] row_mask:0xf bank_mask:0xf bound_ctrl:1
	v_mul_f32_e32 v40, v40, v76
	v_cvt_pk_bf16_f32 v40, v40, v82
	v_mul_f32_dpp v82, v24, v76 quad_perm:[1,0,3,2] row_mask:0xf bank_mask:0xf bound_ctrl:1
	v_mul_f32_e32 v24, v24, v76
	v_cvt_pk_bf16_f32 v24, v24, v82
	v_mul_f32_dpp v82, v8, v76 quad_perm:[1,0,3,2] row_mask:0xf bank_mask:0xf bound_ctrl:1
	v_mul_f32_e32 v8, v8, v76
	v_cvt_pk_bf16_f32 v8, v8, v82
	v_mul_f32_dpp v82, v57, v77 quad_perm:[1,0,3,2] row_mask:0xf bank_mask:0xf bound_ctrl:1
	v_mul_f32_e32 v57, v57, v77
	v_cvt_pk_bf16_f32 v57, v57, v82
	v_mul_f32_dpp v82, v41, v77 quad_perm:[1,0,3,2] row_mask:0xf bank_mask:0xf bound_ctrl:1
	v_mul_f32_e32 v41, v41, v77
	v_cvt_pk_bf16_f32 v41, v41, v82
	v_mul_f32_dpp v82, v25, v77 quad_perm:[1,0,3,2] row_mask:0xf bank_mask:0xf bound_ctrl:1
	v_mul_f32_e32 v25, v25, v77
	v_cvt_pk_bf16_f32 v25, v25, v82
	v_mul_f32_dpp v82, v9, v77 quad_perm:[1,0,3,2] row_mask:0xf bank_mask:0xf bound_ctrl:1
	v_mul_f32_e32 v9, v9, v77
	v_cvt_pk_bf16_f32 v9, v9, v82
	v_mul_f32_dpp v82, v58, v70 quad_perm:[1,0,3,2] row_mask:0xf bank_mask:0xf bound_ctrl:1
	v_mul_f32_e32 v58, v58, v70
	v_cvt_pk_bf16_f32 v58, v58, v82
	v_mul_f32_dpp v82, v42, v70 quad_perm:[1,0,3,2] row_mask:0xf bank_mask:0xf bound_ctrl:1
	v_mul_f32_e32 v42, v42, v70
	v_cvt_pk_bf16_f32 v42, v42, v82
	v_mul_f32_dpp v82, v26, v70 quad_perm:[1,0,3,2] row_mask:0xf bank_mask:0xf bound_ctrl:1
	v_mul_f32_e32 v26, v26, v70
	v_cvt_pk_bf16_f32 v26, v26, v82
	v_mul_f32_dpp v82, v10, v70 quad_perm:[1,0,3,2] row_mask:0xf bank_mask:0xf bound_ctrl:1
	v_mul_f32_e32 v10, v10, v70
	v_cvt_pk_bf16_f32 v10, v10, v82
	v_mul_f32_dpp v82, v59, v71 quad_perm:[1,0,3,2] row_mask:0xf bank_mask:0xf bound_ctrl:1
	v_mul_f32_e32 v59, v59, v71
	v_cvt_pk_bf16_f32 v59, v59, v82
	v_mul_f32_dpp v82, v43, v71 quad_perm:[1,0,3,2] row_mask:0xf bank_mask:0xf bound_ctrl:1
	v_mul_f32_e32 v43, v43, v71
	v_cvt_pk_bf16_f32 v43, v43, v82
	v_mul_f32_dpp v82, v27, v71 quad_perm:[1,0,3,2] row_mask:0xf bank_mask:0xf bound_ctrl:1
	v_mul_f32_e32 v27, v27, v71
	v_cvt_pk_bf16_f32 v27, v27, v82
	v_mul_f32_dpp v82, v11, v71 quad_perm:[1,0,3,2] row_mask:0xf bank_mask:0xf bound_ctrl:1
	v_mul_f32_e32 v11, v11, v71
	v_cvt_pk_bf16_f32 v11, v11, v82
	v_mul_f32_dpp v82, v60, v72 quad_perm:[1,0,3,2] row_mask:0xf bank_mask:0xf bound_ctrl:1
	v_mul_f32_e32 v60, v60, v72
	v_cvt_pk_bf16_f32 v60, v60, v82
	v_mul_f32_dpp v82, v44, v72 quad_perm:[1,0,3,2] row_mask:0xf bank_mask:0xf bound_ctrl:1
	v_mul_f32_e32 v44, v44, v72
	v_cvt_pk_bf16_f32 v44, v44, v82
	v_mul_f32_dpp v82, v28, v72 quad_perm:[1,0,3,2] row_mask:0xf bank_mask:0xf bound_ctrl:1
	v_mul_f32_e32 v28, v28, v72
	v_cvt_pk_bf16_f32 v28, v28, v82
	v_mul_f32_dpp v82, v12, v72 quad_perm:[1,0,3,2] row_mask:0xf bank_mask:0xf bound_ctrl:1
	v_mul_f32_e32 v12, v12, v72
	v_cvt_pk_bf16_f32 v12, v12, v82
	v_mul_f32_dpp v82, v61, v73 quad_perm:[1,0,3,2] row_mask:0xf bank_mask:0xf bound_ctrl:1
	v_mul_f32_e32 v61, v61, v73
	v_cvt_pk_bf16_f32 v61, v61, v82
	v_mul_f32_dpp v82, v45, v73 quad_perm:[1,0,3,2] row_mask:0xf bank_mask:0xf bound_ctrl:1
	v_mul_f32_e32 v45, v45, v73
	v_cvt_pk_bf16_f32 v45, v45, v82
	v_mul_f32_dpp v82, v29, v73 quad_perm:[1,0,3,2] row_mask:0xf bank_mask:0xf bound_ctrl:1
	v_mul_f32_e32 v29, v29, v73
	v_cvt_pk_bf16_f32 v29, v29, v82
	v_mul_f32_dpp v82, v13, v73 quad_perm:[1,0,3,2] row_mask:0xf bank_mask:0xf bound_ctrl:1
	v_mul_f32_e32 v13, v13, v73
	v_cvt_pk_bf16_f32 v13, v13, v82
	v_mul_f32_dpp v82, v62, v66 quad_perm:[1,0,3,2] row_mask:0xf bank_mask:0xf bound_ctrl:1
	v_mul_f32_e32 v62, v62, v66
	v_cvt_pk_bf16_f32 v62, v62, v82
	v_mul_f32_dpp v82, v46, v66 quad_perm:[1,0,3,2] row_mask:0xf bank_mask:0xf bound_ctrl:1
	v_mul_f32_e32 v46, v46, v66
	v_cvt_pk_bf16_f32 v46, v46, v82
	v_mul_f32_dpp v82, v30, v66 quad_perm:[1,0,3,2] row_mask:0xf bank_mask:0xf bound_ctrl:1
	v_mul_f32_e32 v30, v30, v66
	v_cvt_pk_bf16_f32 v30, v30, v82
	v_mul_f32_dpp v82, v14, v66 quad_perm:[1,0,3,2] row_mask:0xf bank_mask:0xf bound_ctrl:1
	v_mul_f32_e32 v14, v14, v66
	v_cvt_pk_bf16_f32 v14, v14, v82
	v_mul_f32_dpp v82, v63, v67 quad_perm:[1,0,3,2] row_mask:0xf bank_mask:0xf bound_ctrl:1
	v_mul_f32_e32 v63, v63, v67
	v_cvt_pk_bf16_f32 v63, v63, v82
	v_mul_f32_dpp v82, v47, v67 quad_perm:[1,0,3,2] row_mask:0xf bank_mask:0xf bound_ctrl:1
	v_mul_f32_e32 v47, v47, v67
	v_cvt_pk_bf16_f32 v47, v47, v82
	v_mul_f32_dpp v82, v31, v67 quad_perm:[1,0,3,2] row_mask:0xf bank_mask:0xf bound_ctrl:1
	v_mul_f32_e32 v31, v31, v67
	v_cvt_pk_bf16_f32 v31, v31, v82
	v_mul_f32_dpp v82, v15, v67 quad_perm:[1,0,3,2] row_mask:0xf bank_mask:0xf bound_ctrl:1
	v_mul_f32_e32 v15, v15, v67
	v_cvt_pk_bf16_f32 v15, v15, v82
	v_mul_f32_dpp v82, v64, v68 quad_perm:[1,0,3,2] row_mask:0xf bank_mask:0xf bound_ctrl:1
	v_mul_f32_e32 v64, v64, v68
	v_cvt_pk_bf16_f32 v64, v64, v82
	v_mul_f32_dpp v82, v48, v68 quad_perm:[1,0,3,2] row_mask:0xf bank_mask:0xf bound_ctrl:1
	v_mul_f32_e32 v48, v48, v68
	v_cvt_pk_bf16_f32 v48, v48, v82
	v_mul_f32_dpp v82, v32, v68 quad_perm:[1,0,3,2] row_mask:0xf bank_mask:0xf bound_ctrl:1
	v_mul_f32_e32 v32, v32, v68
	v_cvt_pk_bf16_f32 v32, v32, v82
	v_mul_f32_dpp v82, v16, v68 quad_perm:[1,0,3,2] row_mask:0xf bank_mask:0xf bound_ctrl:1
	v_mul_f32_e32 v16, v16, v68
	v_cvt_pk_bf16_f32 v16, v16, v82
	v_mul_f32_dpp v82, v65, v69 quad_perm:[1,0,3,2] row_mask:0xf bank_mask:0xf bound_ctrl:1
	v_mul_f32_e32 v65, v65, v69
	v_cvt_pk_bf16_f32 v65, v65, v82
	v_mul_f32_dpp v82, v49, v69 quad_perm:[1,0,3,2] row_mask:0xf bank_mask:0xf bound_ctrl:1
	v_mul_f32_e32 v49, v49, v69
	v_cvt_pk_bf16_f32 v49, v49, v82
	v_mul_f32_dpp v82, v33, v69 quad_perm:[1,0,3,2] row_mask:0xf bank_mask:0xf bound_ctrl:1
	v_mul_f32_e32 v33, v33, v69
	v_cvt_pk_bf16_f32 v33, v33, v82
	v_mul_f32_dpp v82, v17, v69 quad_perm:[1,0,3,2] row_mask:0xf bank_mask:0xf bound_ctrl:1
	v_mul_f32_e32 v17, v17, v69
	v_cvt_pk_bf16_f32 v17, v17, v82
	s_and_saveexec_b64 s[0:1], vcc
	ds_write_b32 v1, v50
	ds_write_b32 v1, v34 offset:64
	ds_write_b32 v1, v18 offset:128
	ds_write_b32 v1, v2 offset:192
	ds_write_b32 v1, v51 offset:256
	ds_write_b32 v1, v35 offset:320
	ds_write_b32 v1, v19 offset:384
	ds_write_b32 v1, v3 offset:448
	ds_write_b32 v1, v52 offset:512
	ds_write_b32 v1, v36 offset:576
	ds_write_b32 v1, v20 offset:640
	ds_write_b32 v1, v4 offset:704
	ds_write_b32 v1, v53 offset:768
	ds_write_b32 v1, v37 offset:832
	ds_write_b32 v1, v21 offset:896
	ds_write_b32 v1, v5 offset:960
	ds_write_b32 v1, v54 offset:2048
	ds_write_b32 v1, v38 offset:2112
	ds_write_b32 v1, v22 offset:2176
	ds_write_b32 v1, v6 offset:2240
	ds_write_b32 v1, v55 offset:2304
	ds_write_b32 v1, v39 offset:2368
	ds_write_b32 v1, v23 offset:2432
	ds_write_b32 v1, v7 offset:2496
	ds_write_b32 v1, v56 offset:2560
	ds_write_b32 v1, v40 offset:2624
	ds_write_b32 v1, v24 offset:2688
	ds_write_b32 v1, v8 offset:2752
	ds_write_b32 v1, v57 offset:2816
	ds_write_b32 v1, v41 offset:2880
	ds_write_b32 v1, v25 offset:2944
	ds_write_b32 v1, v9 offset:3008
	ds_write_b32 v1, v58 offset:4096
	ds_write_b32 v1, v42 offset:4160
	ds_write_b32 v1, v26 offset:4224
	ds_write_b32 v1, v10 offset:4288
	ds_write_b32 v1, v59 offset:4352
	ds_write_b32 v1, v43 offset:4416
	ds_write_b32 v1, v27 offset:4480
	ds_write_b32 v1, v11 offset:4544
	ds_write_b32 v1, v60 offset:4608
	ds_write_b32 v1, v44 offset:4672
	ds_write_b32 v1, v28 offset:4736
	ds_write_b32 v1, v12 offset:4800
	ds_write_b32 v1, v61 offset:4864
	ds_write_b32 v1, v45 offset:4928
	ds_write_b32 v1, v29 offset:4992
	ds_write_b32 v1, v13 offset:5056
	ds_write_b32 v1, v62 offset:6144
	ds_write_b32 v1, v46 offset:6208
	ds_write_b32 v1, v30 offset:6272
	ds_write_b32 v1, v14 offset:6336
	ds_write_b32 v1, v63 offset:6400
	ds_write_b32 v1, v47 offset:6464
	ds_write_b32 v1, v31 offset:6528
	ds_write_b32 v1, v15 offset:6592
	ds_write_b32 v1, v64 offset:6656
	ds_write_b32 v1, v48 offset:6720
	ds_write_b32 v1, v32 offset:6784
	ds_write_b32 v1, v16 offset:6848
	ds_write_b32 v1, v65 offset:6912
	ds_write_b32 v1, v49 offset:6976
	ds_write_b32 v1, v33 offset:7040
	ds_write_b32 v1, v17 offset:7104
	s_or_b64 exec, exec, s[0:1]
	s_lshl_b64 s[0:1], s[96:97], 12
	v_readlane_b32 s8, v245, 30
	v_readlane_b32 s9, v245, 31
	s_add_u32 s0, s8, s0
	s_addc_u32 s1, s9, s1
	v_and_b32_e32 v162, 0xf0, v179
	s_add_u32 s3, s0, s34
	v_lshrrev_b32_e32 v1, 4, v169
	v_add_u32_e32 v10, s2, v162
	s_addc_u32 s8, s1, s35
	s_ashr_i32 s5, s4, 31
	s_waitcnt lgkmcnt(0)
	v_lshl_add_u32 v2, v1, 8, v10
	s_lshl_b64 s[0:1], s[4:5], 12
	ds_read_b128 v[2:5], v2
	s_add_u32 s0, s3, s0
	s_addc_u32 s1, s8, s1
	v_lshl_add_u64 v[6:7], s[0:1], 0, v[162:163]
	v_lshlrev_b32_e32 v162, 12, v1
	v_lshl_add_u64 v[8:9], v[6:7], 0, v[162:163]
	s_waitcnt lgkmcnt(0)
	global_store_dwordx4 v[8:9], v[2:5], off offset:2560
	v_or_b32_e32 v8, 4, v1
	v_lshlrev_b32_e32 v162, 12, v8
	v_lshl_add_u32 v2, v8, 8, v10
	ds_read_b128 v[2:5], v2
	v_lshl_add_u64 v[8:9], v[6:7], 0, v[162:163]
	s_waitcnt lgkmcnt(0)
	global_store_dwordx4 v[8:9], v[2:5], off offset:2560
	v_or_b32_e32 v8, 8, v1
	s_nop 0
	v_lshl_add_u32 v2, v8, 8, v10
	ds_read_b128 v[2:5], v2
	v_lshlrev_b32_e32 v162, 12, v8
	v_lshl_add_u64 v[8:9], v[6:7], 0, v[162:163]
	s_waitcnt lgkmcnt(0)
	global_store_dwordx4 v[8:9], v[2:5], off offset:2560
	v_or_b32_e32 v8, 12, v1
	s_nop 0
	v_lshl_add_u32 v2, v8, 8, v10
	ds_read_b128 v[2:5], v2
	v_lshlrev_b32_e32 v162, 12, v8
	v_lshl_add_u64 v[8:9], v[6:7], 0, v[162:163]
	s_waitcnt lgkmcnt(0)
	global_store_dwordx4 v[8:9], v[2:5], off offset:2560
	v_or_b32_e32 v8, 16, v1
	s_nop 0
	v_lshl_add_u32 v2, v8, 8, v10
	ds_read_b128 v[2:5], v2
	v_lshlrev_b32_e32 v162, 12, v8
	v_lshl_add_u64 v[8:9], v[6:7], 0, v[162:163]
	s_waitcnt lgkmcnt(0)
	global_store_dwordx4 v[8:9], v[2:5], off offset:2560
	v_or_b32_e32 v8, 20, v1
	s_nop 0
	v_lshl_add_u32 v2, v8, 8, v10
	ds_read_b128 v[2:5], v2
	v_lshlrev_b32_e32 v162, 12, v8
	v_lshl_add_u64 v[8:9], v[6:7], 0, v[162:163]
	s_waitcnt lgkmcnt(0)
	global_store_dwordx4 v[8:9], v[2:5], off offset:2560
	v_or_b32_e32 v8, 24, v1
	s_nop 0
	v_lshl_add_u32 v2, v8, 8, v10
	ds_read_b128 v[2:5], v2
	v_lshlrev_b32_e32 v162, 12, v8
	v_lshl_add_u64 v[8:9], v[6:7], 0, v[162:163]
	v_or_b32_e32 v1, 28, v1
	v_lshlrev_b32_e32 v162, 12, v1
	s_waitcnt lgkmcnt(0)
	global_store_dwordx4 v[8:9], v[2:5], off offset:2560
	v_lshl_add_u64 v[6:7], v[6:7], 0, v[162:163]
	s_nop 0
	v_lshl_add_u32 v2, v1, 8, v10
	ds_read_b128 v[2:5], v2
	s_waitcnt lgkmcnt(0)
	global_store_dwordx4 v[6:7], v[2:5], off offset:2560
	s_barrier
	s_and_saveexec_b64 s[0:1], s[36:37]
	s_cbranch_execz .LBB0_802
	s_waitcnt vmcnt(8)
	v_mov_b32_e32 v168, v247
	v_readlane_b32 s2, v243, 55
	s_nop 1
	v_mov_b32_e32 v1, s2
	ds_write_b32 v1, v168

.LBB0_815:
	v_mov_b32_e32 v1, 0
	s_and_saveexec_b64 s[0:1], s[36:37]
	s_cbranch_execz .LBB0_819
	s_mov_b64 s[18:19], exec
	v_mbcnt_lo_u32_b32 v1, s18, 0
	v_mbcnt_hi_u32_b32 v1, s19, v1
	v_cmp_eq_u32_e32 vcc, 0, v1
	s_and_saveexec_b64 s[2:3], vcc
	s_cbranch_execz .LBB0_818
	s_bcnt1_i32_b64 s8, s[18:19]
	v_mov_b32_e32 v2, s8
	global_atomic_add v247, v163, v2, s[4:5] sc0
.LBB0_818:
	s_or_b64 exec, exec, s[2:3]
.LBB0_819:
	s_or_b64 exec, exec, s[0:1]
	s_abs_i32 s0, s13
	v_readlane_b32 s1, v243, 2
	s_mul_hi_u32 s1, s0, s1
	v_readlane_b32 s18, v243, 1
	s_mul_i32 s2, s1, s18
	s_sub_i32 s0, s0, s2
	s_ashr_i32 s9, s13, 31
	s_add_i32 s2, s1, 1
	s_sub_i32 s3, s0, s18
	s_cmp_ge_u32 s0, s18
	s_cselect_b32 s1, s2, s1
	s_cselect_b32 s0, s3, s0
	s_add_i32 s2, s1, 1
	s_cmp_ge_u32 s0, s18
	s_cselect_b32 s0, s2, s1
	s_xor_b32 s11, s0, s9
	s_sub_i32 s8, s11, s9
	s_mul_i32 s0, s8, s18
	v_readlane_b32 s1, v245, 13
	s_sub_i32 s0, s13, s0
	s_mul_i32 s1, s18, s1
	s_add_i32 s0, s0, s1
	s_ashr_i32 s1, s0, 31
	s_lshr_b32 s1, s1, 29
	s_add_i32 s1, s0, s1
	s_ashr_i32 s20, s1, 3
	s_and_b32 s1, s1, -8
	s_lshl_b32 s3, s8, 8
	s_sub_i32 s28, s0, s1
	s_ashr_i32 s21, s20, 31
	s_sub_i32 s3, 0x700, s3
	s_and_b32 s2, s28, 1
	s_lshl_b64 s[0:1], s[20:21], 11
	s_ashr_i32 s13, s3, 31
	s_add_u32 s18, s0, s3
	s_addc_u32 s19, s1, s13
	s_mul_i32 s0, s19, 0x3000
	s_mul_hi_u32 s1, s18, 0x3000
	s_add_i32 s1, s1, s0
	s_mul_i32 s0, s18, 0x3000
	v_readlane_b32 s25, v245, 14
	s_add_u32 s13, s25, s0
	v_readlane_b32 s26, v245, 15
	s_addc_u32 s21, s26, s1
	s_lshl_b32 s0, s28, 6
	s_and_b32 s0, s0, 0xffffff80
	s_ashr_i32 s1, s0, 31
	s_lshl_b64 s[22:23], s[0:1], 1
	s_add_u32 s0, s13, s22
	s_addc_u32 s1, s21, s23
	s_lshl_b32 s2, s2, 7
	v_mov_b32_e32 v150, v0
	s_add_u32 s0, s0, s2
	s_addc_u32 s1, s1, 0
	s_waitcnt vmcnt(8)
	v_ashrrev_i32_e32 v158, 4, v150
	s_mul_hi_i32 s13, s20, 0x1800000
	s_mul_i32 s20, s20, 0x1800000
	v_lshlrev_b32_e32 v2, 3, v150
	v_and_b32_e32 v4, 0xfffff0, v158
	v_lshlrev_b32_e32 v5, 1, v158
	s_add_u32 s20, s25, s20
	v_and_b32_e32 v3, 0x78, v2
	v_and_or_b32 v4, v5, 8, v4
	v_lshrrev_b32_e32 v5, 1, v158
	v_and_b32_e32 v6, 3, v158
	v_add_u32_e32 v8, 32, v158
	s_addc_u32 s13, s26, s13
	v_and_or_b32 v5, v5, 4, v6
	v_lshlrev_b32_e32 v50, 1, v3
	v_and_b32_e32 v3, 0xfffff0, v8
	v_lshlrev_b32_e32 v6, 1, v8
	s_add_u32 s22, s20, s22
	v_and_or_b32 v3, v6, 8, v3
	s_addc_u32 s23, s13, s23
	v_readfirstlane_b32 s13, v150
	v_lshrrev_b32_e32 v4, 1, v4
	v_bfe_u32 v2, v2, 5, 2
	v_lshrrev_b32_e32 v3, 1, v3
	s_ashr_i32 s29, s13, 6
	v_or_b32_e32 v4, v4, v2
	v_or_b32_e32 v2, v3, v2
	v_and_b32_e32 v151, 31, v150
	v_lshlrev_b32_e32 v6, 9, v2
	v_lshlrev_b32_e32 v2, 8, v158
	v_and_b32_e32 v3, 0xf0, v150
	s_lshl_b32 s34, s29, 5
	v_bfe_u32 v152, v150, 5, 1
	v_bitop3_b32 v20, v50, v2, v3 bitop3:0xde
	v_or_b32_e32 v7, s34, v151
	v_mov_b64_e32 v[2:3], s[0:1]
	v_mad_i64_i32 v[2:3], s[0:1], v7, s33, v[2:3]
	v_lshlrev_b32_e32 v162, 4, v152
	v_lshl_add_u64 v[2:3], v[2:3], 0, v[162:163]
	v_lshlrev_b32_e32 v4, 9, v4
	v_lshlrev_b32_e32 v5, 6, v5
	global_load_dwordx4 v[110:113], v[2:3], off
	global_load_dwordx4 v[106:109], v[2:3], off offset:32
	global_load_dwordx4 v[102:105], v[2:3], off offset:64
	global_load_dwordx4 v[98:101], v[2:3], off offset:96
	v_and_b32_e32 v2, 48, v50
	v_lshlrev_b32_e32 v52, 2, v152
	v_or3_b32 v21, v4, v5, v2
	v_or3_b32 v22, v6, v5, v2
	s_add_i32 s25, s34, s3
	v_sub_u32_e32 v2, v151, v52
	v_add_u32_e32 v156, s25, v2
	v_mov_b64_e32 v[2:3], s[22:23]
	v_mad_i64_i32 v[4:5], s[0:1], v158, s33, v[2:3]
	v_mov_b32_e32 v51, v163
	v_mad_i64_i32 v[8:9], s[0:1], v8, s33, v[2:3]
	v_lshl_add_u64 v[12:13], v[4:5], 0, v[50:51]
	v_lshl_add_u64 v[16:17], v[8:9], 0, v[50:51]
	global_load_dwordx4 v[4:7], v[12:13], off offset:2048
	global_load_dwordx4 v[8:11], v[16:17], off offset:2048
	s_nop 0
	global_load_dwordx4 v[12:15], v[12:13], off offset:1024
	s_nop 0
	global_load_dwordx4 v[16:19], v[16:17], off offset:1024
	v_add_u32_e32 v164, 0, v20
	v_add_u32_e32 v165, 0, v21
	v_add_u32_e32 v166, 0, v22
	s_waitcnt vmcnt(1)
	ds_write_b128 v164, v[12:15] offset:32768
	s_waitcnt vmcnt(0)
	ds_write_b128 v164, v[16:19] offset:40960
	ds_write_b128 v165, v[4:7]
	v_add_u32_e32 v4, 64, v158
	v_add_u32_e32 v6, 0x60, v158
	v_mad_i64_i32 v[4:5], s[0:1], v4, s33, v[2:3]
	v_mad_i64_i32 v[2:3], s[0:1], v6, s33, v[2:3]
	v_lshl_add_u64 v[4:5], v[4:5], 0, v[50:51]
	v_lshl_add_u64 v[2:3], v[2:3], 0, v[50:51]
	ds_write_b128 v166, v[8:11]
	s_waitcnt lgkmcnt(0)
	s_barrier
	global_load_dwordx4 v[34:37], v[4:5], off offset:2048
	global_load_dwordx4 v[38:41], v[2:3], off offset:2048
	global_load_dwordx4 v[42:45], v[4:5], off offset:1024
	global_load_dwordx4 v[46:49], v[2:3], off offset:1024
	v_lshlrev_b32_e32 v148, 4, v150
	s_add_i32 s2, s2, 0
	s_movk_i32 s0, 0xf0
	v_lshlrev_b32_e32 v51, 8, v151
	v_xor_b32_e32 v162, s2, v162
	v_bitop3_b32 v2, v162, v148, s0 bitop3:0x78
	v_add_u32_e32 v159, v51, v2
	ds_read_b128 v[2:5], v159 offset:32768
	v_and_b32_e32 v53, 0xf0, v148
	v_bitop3_b32 v6, v162, v53, 32 bitop3:0x36
	v_add_u32_e32 v160, v51, v6
	ds_read_b128 v[54:57], v160 offset:32768
	v_bitop3_b32 v58, v162, v53, 64 bitop3:0x36
	s_waitcnt lgkmcnt(1)
	v_mfma_f32_32x32x16_bf16 v[18:33], v[2:5], v[110:113], 0
	ds_read_b128 v[2:5], v159 offset:40960
	v_add_u32_e32 v161, v51, v58
	s_movk_i32 s0, 0x60
	v_bitop3_b32 v53, v162, v53, s0 bitop3:0x36
	v_add_u32_e32 v162, v51, v53
	s_cmp_gt_i32 s25, 62
	s_waitcnt lgkmcnt(1)
	v_mfma_f32_32x32x16_bf16 v[18:33], v[54:57], v[106:109], v[18:33]
	ds_read_b128 v[54:57], v160 offset:40960
	s_waitcnt lgkmcnt(1)
	v_mfma_f32_32x32x16_bf16 v[2:17], v[2:5], v[110:113], 0
	s_waitcnt lgkmcnt(0)
	v_mfma_f32_32x32x16_bf16 v[2:17], v[54:57], v[106:109], v[2:17]
	ds_read_b128 v[54:57], v161 offset:32768
	s_waitcnt lgkmcnt(0)
	v_mfma_f32_32x32x16_bf16 v[18:33], v[54:57], v[102:105], v[18:33]
	ds_read_b128 v[54:57], v161 offset:40960
	s_waitcnt lgkmcnt(0)
	v_mfma_f32_32x32x16_bf16 v[2:17], v[54:57], v[102:105], v[2:17]
	ds_read_b128 v[54:57], v162 offset:32768
	s_waitcnt lgkmcnt(0)
	v_mfma_f32_32x32x16_bf16 v[18:33], v[54:57], v[98:101], v[18:33]
	ds_read_b128 v[54:57], v162 offset:40960
	s_waitcnt lgkmcnt(0)
	v_mfma_f32_32x32x16_bf16 v[2:17], v[54:57], v[98:101], v[2:17]
	s_cbranch_scc1 .LBB0_821
	v_cmp_gt_i32_e64 s[90:91], 26, v156
	v_cmp_gt_i32_e64 s[92:93], 27, v156
	v_cmp_gt_i32_e64 s[88:89], 25, v156
	s_and_b64 s[90:91], s[92:93], s[90:91]
	v_cmp_gt_i32_e64 s[86:87], 24, v156
	s_and_b64 s[88:89], s[90:91], s[88:89]
	v_cmp_gt_i32_e64 s[84:85], 19, v156
	s_and_b64 s[86:87], s[88:89], s[86:87]
	v_cmp_gt_i32_e64 s[82:83], 18, v156
	s_and_b64 s[84:85], s[86:87], s[84:85]
	v_cmp_gt_i32_e64 s[80:81], 17, v156
	s_and_b64 s[82:83], s[84:85], s[82:83]
	v_cmp_gt_i32_e64 s[78:79], 16, v156
	s_and_b64 s[80:81], s[82:83], s[80:81]
	v_cmp_gt_i32_e64 s[76:77], 11, v156
	s_and_b64 s[78:79], s[80:81], s[78:79]
	v_cmp_gt_i32_e64 s[74:75], 10, v156
	s_and_b64 s[76:77], s[78:79], s[76:77]
	v_cmp_gt_i32_e64 s[72:73], 9, v156
	s_and_b64 s[74:75], s[76:77], s[74:75]
	v_cmp_gt_i32_e64 s[70:71], 8, v156
	s_and_b64 s[72:73], s[74:75], s[72:73]
	v_cmp_gt_i32_e64 s[68:69], 3, v156
	s_and_b64 s[70:71], s[72:73], s[70:71]
	v_cmp_gt_i32_e64 s[66:67], 2, v156
	s_and_b64 s[68:69], s[70:71], s[68:69]
	v_cmp_gt_i32_e64 s[2:3], 1, v156
	s_and_b64 s[66:67], s[68:69], s[66:67]
	v_cmp_gt_i32_e64 s[0:1], 0, v156
	s_and_b64 s[2:3], s[66:67], s[2:3]
	s_and_b64 s[0:1], s[2:3], s[0:1]
	v_cmp_gt_i32_e64 s[64:65], 58, v156
	v_cndmask_b32_e64 v18, v18, v175, s[0:1]
	v_cmp_gt_i32_e64 s[0:1], 59, v156
	v_cmp_gt_i32_e64 s[62:63], 57, v156
	v_cmp_gt_i32_e64 s[60:61], 56, v156
	v_cndmask_b32_e64 v17, v17, v175, s[0:1]
	s_and_b64 s[0:1], s[0:1], s[64:65]
	v_cndmask_b32_e64 v16, v16, v175, s[0:1]
	s_and_b64 s[0:1], s[0:1], s[62:63]
	v_cmp_gt_i32_e64 s[58:59], 51, v156
	v_cndmask_b32_e64 v15, v15, v175, s[0:1]
	s_and_b64 s[0:1], s[0:1], s[60:61]
	v_cmp_gt_i32_e64 s[56:57], 50, v156
	v_cndmask_b32_e64 v14, v14, v175, s[0:1]
	s_and_b64 s[0:1], s[0:1], s[58:59]
	v_cmp_gt_i32_e64 s[54:55], 49, v156
	v_cndmask_b32_e64 v13, v13, v175, s[0:1]
	s_and_b64 s[0:1], s[0:1], s[56:57]
	v_cmp_gt_i32_e64 s[52:53], 48, v156
	v_cndmask_b32_e64 v12, v12, v175, s[0:1]
	s_and_b64 s[0:1], s[0:1], s[54:55]
	v_cmp_gt_i32_e64 s[50:51], 43, v156
	v_cndmask_b32_e64 v11, v11, v175, s[0:1]
	s_and_b64 s[0:1], s[0:1], s[52:53]
	v_cmp_gt_i32_e64 s[48:49], 42, v156
	v_cndmask_b32_e64 v10, v10, v175, s[0:1]
	s_and_b64 s[0:1], s[0:1], s[50:51]
	v_cmp_gt_i32_e64 s[46:47], 41, v156
	v_cndmask_b32_e64 v9, v9, v175, s[0:1]
	s_and_b64 s[0:1], s[0:1], s[48:49]
	v_cmp_gt_i32_e64 s[44:45], 40, v156
	v_cndmask_b32_e64 v8, v8, v175, s[0:1]
	s_and_b64 s[0:1], s[0:1], s[46:47]
	v_cmp_gt_i32_e64 s[42:43], 35, v156
	v_cndmask_b32_e64 v7, v7, v175, s[0:1]
	s_and_b64 s[0:1], s[0:1], s[44:45]
	v_cmp_gt_i32_e64 s[40:41], 34, v156
	v_cndmask_b32_e64 v6, v6, v175, s[0:1]
	s_and_b64 s[0:1], s[0:1], s[42:43]
	v_cmp_gt_i32_e64 s[38:39], 33, v156
	v_cndmask_b32_e64 v5, v5, v175, s[0:1]
	s_and_b64 s[0:1], s[0:1], s[40:41]
	v_cmp_gt_i32_e32 vcc, 32, v156
	v_cndmask_b32_e64 v4, v4, v175, s[0:1]
	s_and_b64 s[0:1], s[0:1], s[38:39]
	s_and_b64 vcc, s[0:1], vcc
	v_cndmask_b32_e64 v33, v33, v175, s[92:93]
	v_cndmask_b32_e64 v32, v32, v175, s[90:91]
	v_cndmask_b32_e64 v31, v31, v175, s[88:89]
	v_cndmask_b32_e64 v30, v30, v175, s[86:87]
	v_cndmask_b32_e64 v29, v29, v175, s[84:85]
	v_cndmask_b32_e64 v28, v28, v175, s[82:83]
	v_cndmask_b32_e64 v27, v27, v175, s[80:81]
	v_cndmask_b32_e64 v26, v26, v175, s[78:79]
	v_cndmask_b32_e64 v25, v25, v175, s[76:77]
	v_cndmask_b32_e64 v24, v24, v175, s[74:75]
	v_cndmask_b32_e64 v23, v23, v175, s[72:73]
	v_cndmask_b32_e64 v22, v22, v175, s[70:71]
	v_cndmask_b32_e64 v21, v21, v175, s[68:69]
	v_cndmask_b32_e64 v20, v20, v175, s[66:67]
	v_cndmask_b32_e64 v19, v19, v175, s[2:3]
	v_cndmask_b32_e64 v3, v3, v175, s[0:1]
	v_cndmask_b32_e32 v2, v2, v175, vcc

.Lmskip_dif_6:
	v_cmp_gt_u32_e32 vcc, 32, v149
	s_and_saveexec_b64 s[0:1], vcc
	v_add_f32_e32 v68, v98, v99
	v_fmac_f32_e32 v68, v157, v114
	v_add_f32_e32 v66, v66, v67
	v_fmac_f32_e32 v66, v68, v100
	ds_write_b32 v155, v66
	s_or_b64 exec, exec, s[0:1]
	s_waitcnt lgkmcnt(0)
	ds_read_b128 v[78:81], v154
	ds_read_b128 v[74:77], v154 offset:32
	ds_read_b128 v[70:73], v154 offset:64
	ds_read_b128 v[66:69], v154 offset:96
	s_lshl_b32 s0, s29, 13
	s_waitcnt lgkmcnt(3)
	v_rcp_f32_e32 v82, v78
	v_and_b32_e32 v78, 1, v150
	s_add_i32 s2, s0, 0
	v_cmp_eq_u32_e32 vcc, 0, v78
	v_lshlrev_b32_e32 v78, 10, v152
	v_lshlrev_b32_e32 v83, 1, v151
	v_add3_u32 v78, s2, v78, v83
	s_waitcnt lgkmcnt(0)
	s_barrier
	v_rcp_f32_e32 v66, v66
	v_rcp_f32_e32 v67, v67
	v_rcp_f32_e32 v68, v68
	v_rcp_f32_e32 v69, v69
	v_rcp_f32_e32 v70, v70
	v_rcp_f32_e32 v71, v71
	v_rcp_f32_e32 v72, v72
	v_rcp_f32_e32 v73, v73
	v_rcp_f32_e32 v74, v74
	v_rcp_f32_e32 v75, v75
	v_rcp_f32_e32 v76, v76
	v_rcp_f32_e32 v77, v77
	v_rcp_f32_e32 v79, v79
	v_rcp_f32_e32 v80, v80
	v_rcp_f32_e32 v81, v81
	s_nop 1
	v_mul_f32_dpp v83, v50, v82 quad_perm:[1,0,3,2] row_mask:0xf bank_mask:0xf bound_ctrl:1
	v_mul_f32_e32 v50, v50, v82
	v_cvt_pk_bf16_f32 v50, v50, v83
	v_mul_f32_dpp v83, v34, v82 quad_perm:[1,0,3,2] row_mask:0xf bank_mask:0xf bound_ctrl:1
	v_mul_f32_e32 v34, v34, v82
	v_cvt_pk_bf16_f32 v34, v34, v83
	v_mul_f32_dpp v83, v18, v82 quad_perm:[1,0,3,2] row_mask:0xf bank_mask:0xf bound_ctrl:1
	v_mul_f32_e32 v18, v18, v82
	v_cvt_pk_bf16_f32 v18, v18, v83
	v_mul_f32_dpp v83, v2, v82 quad_perm:[1,0,3,2] row_mask:0xf bank_mask:0xf bound_ctrl:1
	v_mul_f32_e32 v2, v2, v82
	v_cvt_pk_bf16_f32 v2, v2, v83
	v_mul_f32_dpp v83, v51, v79 quad_perm:[1,0,3,2] row_mask:0xf bank_mask:0xf bound_ctrl:1
	v_mul_f32_e32 v51, v51, v79
	v_cvt_pk_bf16_f32 v51, v51, v83
	v_mul_f32_dpp v83, v35, v79 quad_perm:[1,0,3,2] row_mask:0xf bank_mask:0xf bound_ctrl:1
	v_mul_f32_e32 v35, v35, v79
	v_cvt_pk_bf16_f32 v35, v35, v83
	v_mul_f32_dpp v83, v19, v79 quad_perm:[1,0,3,2] row_mask:0xf bank_mask:0xf bound_ctrl:1
	v_mul_f32_e32 v19, v19, v79
	v_cvt_pk_bf16_f32 v19, v19, v83
	v_mul_f32_dpp v83, v3, v79 quad_perm:[1,0,3,2] row_mask:0xf bank_mask:0xf bound_ctrl:1
	v_mul_f32_e32 v3, v3, v79
	v_cvt_pk_bf16_f32 v3, v3, v83
	v_mul_f32_dpp v83, v52, v80 quad_perm:[1,0,3,2] row_mask:0xf bank_mask:0xf bound_ctrl:1
	v_mul_f32_e32 v52, v52, v80
	v_cvt_pk_bf16_f32 v52, v52, v83
	v_mul_f32_dpp v83, v36, v80 quad_perm:[1,0,3,2] row_mask:0xf bank_mask:0xf bound_ctrl:1
	v_mul_f32_e32 v36, v36, v80
	v_cvt_pk_bf16_f32 v36, v36, v83
	v_mul_f32_dpp v83, v20, v80 quad_perm:[1,0,3,2] row_mask:0xf bank_mask:0xf bound_ctrl:1
	v_mul_f32_e32 v20, v20, v80
	v_cvt_pk_bf16_f32 v20, v20, v83
	v_mul_f32_dpp v83, v4, v80 quad_perm:[1,0,3,2] row_mask:0xf bank_mask:0xf bound_ctrl:1
	v_mul_f32_e32 v4, v4, v80
	v_cvt_pk_bf16_f32 v4, v4, v83
	v_mul_f32_dpp v83, v53, v81 quad_perm:[1,0,3,2] row_mask:0xf bank_mask:0xf bound_ctrl:1
	v_mul_f32_e32 v53, v53, v81
	v_cvt_pk_bf16_f32 v53, v53, v83
	v_mul_f32_dpp v83, v37, v81 quad_perm:[1,0,3,2] row_mask:0xf bank_mask:0xf bound_ctrl:1
	v_mul_f32_e32 v37, v37, v81
	v_cvt_pk_bf16_f32 v37, v37, v83
	v_mul_f32_dpp v83, v21, v81 quad_perm:[1,0,3,2] row_mask:0xf bank_mask:0xf bound_ctrl:1
	v_mul_f32_e32 v21, v21, v81
	v_cvt_pk_bf16_f32 v21, v21, v83
	v_mul_f32_dpp v83, v5, v81 quad_perm:[1,0,3,2] row_mask:0xf bank_mask:0xf bound_ctrl:1
	v_mul_f32_e32 v5, v5, v81
	v_cvt_pk_bf16_f32 v5, v5, v83
	v_mul_f32_dpp v83, v54, v74 quad_perm:[1,0,3,2] row_mask:0xf bank_mask:0xf bound_ctrl:1
	v_mul_f32_e32 v54, v54, v74
	v_cvt_pk_bf16_f32 v54, v54, v83
	v_mul_f32_dpp v83, v38, v74 quad_perm:[1,0,3,2] row_mask:0xf bank_mask:0xf bound_ctrl:1
	v_mul_f32_e32 v38, v38, v74
	v_cvt_pk_bf16_f32 v38, v38, v83
	v_mul_f32_dpp v83, v22, v74 quad_perm:[1,0,3,2] row_mask:0xf bank_mask:0xf bound_ctrl:1
	v_mul_f32_e32 v22, v22, v74
	v_cvt_pk_bf16_f32 v22, v22, v83
	v_mul_f32_dpp v83, v6, v74 quad_perm:[1,0,3,2] row_mask:0xf bank_mask:0xf bound_ctrl:1
	v_mul_f32_e32 v6, v6, v74
	v_cvt_pk_bf16_f32 v6, v6, v83
	v_mul_f32_dpp v83, v55, v75 quad_perm:[1,0,3,2] row_mask:0xf bank_mask:0xf bound_ctrl:1
	v_mul_f32_e32 v55, v55, v75
	v_cvt_pk_bf16_f32 v55, v55, v83
	v_mul_f32_dpp v83, v39, v75 quad_perm:[1,0,3,2] row_mask:0xf bank_mask:0xf bound_ctrl:1
	v_mul_f32_e32 v39, v39, v75
	v_cvt_pk_bf16_f32 v39, v39, v83
	v_mul_f32_dpp v83, v23, v75 quad_perm:[1,0,3,2] row_mask:0xf bank_mask:0xf bound_ctrl:1
	v_mul_f32_e32 v23, v23, v75
	v_cvt_pk_bf16_f32 v23, v23, v83
	v_mul_f32_dpp v83, v7, v75 quad_perm:[1,0,3,2] row_mask:0xf bank_mask:0xf bound_ctrl:1
	v_mul_f32_e32 v7, v7, v75
	v_cvt_pk_bf16_f32 v7, v7, v83
	v_mul_f32_dpp v83, v56, v76 quad_perm:[1,0,3,2] row_mask:0xf bank_mask:0xf bound_ctrl:1
	v_mul_f32_e32 v56, v56, v76
	v_cvt_pk_bf16_f32 v56, v56, v83
	v_mul_f32_dpp v83, v40, v76 quad_perm:[1,0,3,2] row_mask:0xf bank_mask:0xf bound_ctrl:1
	v_mul_f32_e32 v40, v40, v76
	v_cvt_pk_bf16_f32 v40, v40, v83
	v_mul_f32_dpp v83, v24, v76 quad_perm:[1,0,3,2] row_mask:0xf bank_mask:0xf bound_ctrl:1
	v_mul_f32_e32 v24, v24, v76
	v_cvt_pk_bf16_f32 v24, v24, v83
	v_mul_f32_dpp v83, v8, v76 quad_perm:[1,0,3,2] row_mask:0xf bank_mask:0xf bound_ctrl:1
	v_mul_f32_e32 v8, v8, v76
	v_cvt_pk_bf16_f32 v8, v8, v83
	v_mul_f32_dpp v83, v57, v77 quad_perm:[1,0,3,2] row_mask:0xf bank_mask:0xf bound_ctrl:1
	v_mul_f32_e32 v57, v57, v77
	v_cvt_pk_bf16_f32 v57, v57, v83
	v_mul_f32_dpp v83, v41, v77 quad_perm:[1,0,3,2] row_mask:0xf bank_mask:0xf bound_ctrl:1
	v_mul_f32_e32 v41, v41, v77
	v_cvt_pk_bf16_f32 v41, v41, v83
	v_mul_f32_dpp v83, v25, v77 quad_perm:[1,0,3,2] row_mask:0xf bank_mask:0xf bound_ctrl:1
	v_mul_f32_e32 v25, v25, v77
	v_cvt_pk_bf16_f32 v25, v25, v83
	v_mul_f32_dpp v83, v9, v77 quad_perm:[1,0,3,2] row_mask:0xf bank_mask:0xf bound_ctrl:1
	v_mul_f32_e32 v9, v9, v77
	v_cvt_pk_bf16_f32 v9, v9, v83
	v_mul_f32_dpp v83, v58, v70 quad_perm:[1,0,3,2] row_mask:0xf bank_mask:0xf bound_ctrl:1
	v_mul_f32_e32 v58, v58, v70
	v_cvt_pk_bf16_f32 v58, v58, v83
	v_mul_f32_dpp v83, v42, v70 quad_perm:[1,0,3,2] row_mask:0xf bank_mask:0xf bound_ctrl:1
	v_mul_f32_e32 v42, v42, v70
	v_cvt_pk_bf16_f32 v42, v42, v83
	v_mul_f32_dpp v83, v26, v70 quad_perm:[1,0,3,2] row_mask:0xf bank_mask:0xf bound_ctrl:1
	v_mul_f32_e32 v26, v26, v70
	v_cvt_pk_bf16_f32 v26, v26, v83
	v_mul_f32_dpp v83, v10, v70 quad_perm:[1,0,3,2] row_mask:0xf bank_mask:0xf bound_ctrl:1
	v_mul_f32_e32 v10, v10, v70
	v_cvt_pk_bf16_f32 v10, v10, v83
	v_mul_f32_dpp v83, v59, v71 quad_perm:[1,0,3,2] row_mask:0xf bank_mask:0xf bound_ctrl:1
	v_mul_f32_e32 v59, v59, v71
	v_cvt_pk_bf16_f32 v59, v59, v83
	v_mul_f32_dpp v83, v43, v71 quad_perm:[1,0,3,2] row_mask:0xf bank_mask:0xf bound_ctrl:1
	v_mul_f32_e32 v43, v43, v71
	v_cvt_pk_bf16_f32 v43, v43, v83
	v_mul_f32_dpp v83, v27, v71 quad_perm:[1,0,3,2] row_mask:0xf bank_mask:0xf bound_ctrl:1
	v_mul_f32_e32 v27, v27, v71
	v_cvt_pk_bf16_f32 v27, v27, v83
	v_mul_f32_dpp v83, v11, v71 quad_perm:[1,0,3,2] row_mask:0xf bank_mask:0xf bound_ctrl:1
	v_mul_f32_e32 v11, v11, v71
	v_cvt_pk_bf16_f32 v11, v11, v83
	v_mul_f32_dpp v83, v60, v72 quad_perm:[1,0,3,2] row_mask:0xf bank_mask:0xf bound_ctrl:1
	v_mul_f32_e32 v60, v60, v72
	v_cvt_pk_bf16_f32 v60, v60, v83
	v_mul_f32_dpp v83, v44, v72 quad_perm:[1,0,3,2] row_mask:0xf bank_mask:0xf bound_ctrl:1
	v_mul_f32_e32 v44, v44, v72
	v_cvt_pk_bf16_f32 v44, v44, v83
	v_mul_f32_dpp v83, v28, v72 quad_perm:[1,0,3,2] row_mask:0xf bank_mask:0xf bound_ctrl:1
	v_mul_f32_e32 v28, v28, v72
	v_cvt_pk_bf16_f32 v28, v28, v83
	v_mul_f32_dpp v83, v12, v72 quad_perm:[1,0,3,2] row_mask:0xf bank_mask:0xf bound_ctrl:1
	v_mul_f32_e32 v12, v12, v72
	v_cvt_pk_bf16_f32 v12, v12, v83
	v_mul_f32_dpp v83, v61, v73 quad_perm:[1,0,3,2] row_mask:0xf bank_mask:0xf bound_ctrl:1
	v_mul_f32_e32 v61, v61, v73
	v_cvt_pk_bf16_f32 v61, v61, v83
	v_mul_f32_dpp v83, v45, v73 quad_perm:[1,0,3,2] row_mask:0xf bank_mask:0xf bound_ctrl:1
	v_mul_f32_e32 v45, v45, v73
	v_cvt_pk_bf16_f32 v45, v45, v83
	v_mul_f32_dpp v83, v29, v73 quad_perm:[1,0,3,2] row_mask:0xf bank_mask:0xf bound_ctrl:1
	v_mul_f32_e32 v29, v29, v73
	v_cvt_pk_bf16_f32 v29, v29, v83
	v_mul_f32_dpp v83, v13, v73 quad_perm:[1,0,3,2] row_mask:0xf bank_mask:0xf bound_ctrl:1
	v_mul_f32_e32 v13, v13, v73
	v_cvt_pk_bf16_f32 v13, v13, v83
	v_mul_f32_dpp v83, v62, v66 quad_perm:[1,0,3,2] row_mask:0xf bank_mask:0xf bound_ctrl:1
	v_mul_f32_e32 v62, v62, v66
	v_cvt_pk_bf16_f32 v62, v62, v83
	v_mul_f32_dpp v83, v46, v66 quad_perm:[1,0,3,2] row_mask:0xf bank_mask:0xf bound_ctrl:1
	v_mul_f32_e32 v46, v46, v66
	v_cvt_pk_bf16_f32 v46, v46, v83
	v_mul_f32_dpp v83, v30, v66 quad_perm:[1,0,3,2] row_mask:0xf bank_mask:0xf bound_ctrl:1
	v_mul_f32_e32 v30, v30, v66
	v_cvt_pk_bf16_f32 v30, v30, v83
	v_mul_f32_dpp v83, v14, v66 quad_perm:[1,0,3,2] row_mask:0xf bank_mask:0xf bound_ctrl:1
	v_mul_f32_e32 v14, v14, v66
	v_cvt_pk_bf16_f32 v14, v14, v83
	v_mul_f32_dpp v83, v63, v67 quad_perm:[1,0,3,2] row_mask:0xf bank_mask:0xf bound_ctrl:1
	v_mul_f32_e32 v63, v63, v67
	v_cvt_pk_bf16_f32 v63, v63, v83
	v_mul_f32_dpp v83, v47, v67 quad_perm:[1,0,3,2] row_mask:0xf bank_mask:0xf bound_ctrl:1
	v_mul_f32_e32 v47, v47, v67
	v_cvt_pk_bf16_f32 v47, v47, v83
	v_mul_f32_dpp v83, v31, v67 quad_perm:[1,0,3,2] row_mask:0xf bank_mask:0xf bound_ctrl:1
	v_mul_f32_e32 v31, v31, v67
	v_cvt_pk_bf16_f32 v31, v31, v83
	v_mul_f32_dpp v83, v15, v67 quad_perm:[1,0,3,2] row_mask:0xf bank_mask:0xf bound_ctrl:1
	v_mul_f32_e32 v15, v15, v67
	v_cvt_pk_bf16_f32 v15, v15, v83
	v_mul_f32_dpp v83, v64, v68 quad_perm:[1,0,3,2] row_mask:0xf bank_mask:0xf bound_ctrl:1
	v_mul_f32_e32 v64, v64, v68
	v_cvt_pk_bf16_f32 v64, v64, v83
	v_mul_f32_dpp v83, v48, v68 quad_perm:[1,0,3,2] row_mask:0xf bank_mask:0xf bound_ctrl:1
	v_mul_f32_e32 v48, v48, v68
	v_cvt_pk_bf16_f32 v48, v48, v83
	v_mul_f32_dpp v83, v32, v68 quad_perm:[1,0,3,2] row_mask:0xf bank_mask:0xf bound_ctrl:1
	v_mul_f32_e32 v32, v32, v68
	v_cvt_pk_bf16_f32 v32, v32, v83
	v_mul_f32_dpp v83, v16, v68 quad_perm:[1,0,3,2] row_mask:0xf bank_mask:0xf bound_ctrl:1
	v_mul_f32_e32 v16, v16, v68
	v_cvt_pk_bf16_f32 v16, v16, v83
	v_mul_f32_dpp v83, v65, v69 quad_perm:[1,0,3,2] row_mask:0xf bank_mask:0xf bound_ctrl:1
	v_mul_f32_e32 v65, v65, v69
	v_cvt_pk_bf16_f32 v65, v65, v83
	v_mul_f32_dpp v83, v49, v69 quad_perm:[1,0,3,2] row_mask:0xf bank_mask:0xf bound_ctrl:1
	v_mul_f32_e32 v49, v49, v69
	v_cvt_pk_bf16_f32 v49, v49, v83
	v_mul_f32_dpp v83, v33, v69 quad_perm:[1,0,3,2] row_mask:0xf bank_mask:0xf bound_ctrl:1
	v_mul_f32_e32 v33, v33, v69
	v_cvt_pk_bf16_f32 v33, v33, v83
	v_mul_f32_dpp v83, v17, v69 quad_perm:[1,0,3,2] row_mask:0xf bank_mask:0xf bound_ctrl:1
	v_mul_f32_e32 v17, v17, v69
	v_cvt_pk_bf16_f32 v17, v17, v83
	s_and_saveexec_b64 s[0:1], vcc
	ds_write_b32 v78, v50
	ds_write_b32 v78, v34 offset:64
	ds_write_b32 v78, v18 offset:128
	ds_write_b32 v78, v2 offset:192
	ds_write_b32 v78, v51 offset:256
	ds_write_b32 v78, v35 offset:320
	ds_write_b32 v78, v19 offset:384
	ds_write_b32 v78, v3 offset:448
	ds_write_b32 v78, v52 offset:512
	ds_write_b32 v78, v36 offset:576
	ds_write_b32 v78, v20 offset:640
	ds_write_b32 v78, v4 offset:704
	ds_write_b32 v78, v53 offset:768
	ds_write_b32 v78, v37 offset:832
	ds_write_b32 v78, v21 offset:896
	ds_write_b32 v78, v5 offset:960
	ds_write_b32 v78, v54 offset:2048
	ds_write_b32 v78, v38 offset:2112
	ds_write_b32 v78, v22 offset:2176
	ds_write_b32 v78, v6 offset:2240
	ds_write_b32 v78, v55 offset:2304
	ds_write_b32 v78, v39 offset:2368
	ds_write_b32 v78, v23 offset:2432
	ds_write_b32 v78, v7 offset:2496
	ds_write_b32 v78, v56 offset:2560
	ds_write_b32 v78, v40 offset:2624
	ds_write_b32 v78, v24 offset:2688
	ds_write_b32 v78, v8 offset:2752
	ds_write_b32 v78, v57 offset:2816
	ds_write_b32 v78, v41 offset:2880
	ds_write_b32 v78, v25 offset:2944
	ds_write_b32 v78, v9 offset:3008
	ds_write_b32 v78, v58 offset:4096
	ds_write_b32 v78, v42 offset:4160
	ds_write_b32 v78, v26 offset:4224
	ds_write_b32 v78, v10 offset:4288
	ds_write_b32 v78, v59 offset:4352
	ds_write_b32 v78, v43 offset:4416
	ds_write_b32 v78, v27 offset:4480
	ds_write_b32 v78, v11 offset:4544
	ds_write_b32 v78, v60 offset:4608
	ds_write_b32 v78, v44 offset:4672
	ds_write_b32 v78, v28 offset:4736
	ds_write_b32 v78, v12 offset:4800
	ds_write_b32 v78, v61 offset:4864
	ds_write_b32 v78, v45 offset:4928
	ds_write_b32 v78, v29 offset:4992
	ds_write_b32 v78, v13 offset:5056
	ds_write_b32 v78, v62 offset:6144
	ds_write_b32 v78, v46 offset:6208
	ds_write_b32 v78, v30 offset:6272
	ds_write_b32 v78, v14 offset:6336
	ds_write_b32 v78, v63 offset:6400
	ds_write_b32 v78, v47 offset:6464
	ds_write_b32 v78, v31 offset:6528
	ds_write_b32 v78, v15 offset:6592
	ds_write_b32 v78, v64 offset:6656
	ds_write_b32 v78, v48 offset:6720
	ds_write_b32 v78, v32 offset:6784
	ds_write_b32 v78, v16 offset:6848
	ds_write_b32 v78, v65 offset:6912
	ds_write_b32 v78, v49 offset:6976
	ds_write_b32 v78, v33 offset:7040
	ds_write_b32 v78, v17 offset:7104
	s_or_b64 exec, exec, s[0:1]
	s_lshl_b64 s[0:1], s[18:19], 11
	v_readlane_b32 s8, v245, 32
	v_readlane_b32 s9, v245, 33
	s_add_u32 s3, s8, s0
	s_addc_u32 s8, s9, s1
	s_lshl_b32 s0, s28, 7
	s_ashr_i32 s1, s0, 31
	s_lshl_b64 s[0:1], s[0:1], 1
	v_and_b32_e32 v162, 0xf0, v148
	s_add_u32 s3, s3, s0
	v_lshrrev_b32_e32 v10, 4, v149
	v_add_u32_e32 v11, s2, v162
	s_addc_u32 s8, s8, s1
	s_ashr_i32 s35, s34, 31
	s_waitcnt lgkmcnt(0)
	v_lshl_add_u32 v2, v10, 8, v11
	s_lshl_b64 s[0:1], s[34:35], 11
	ds_read_b128 v[2:5], v2
	s_add_u32 s0, s3, s0
	s_addc_u32 s1, s8, s1
	v_lshl_add_u64 v[6:7], s[0:1], 0, v[162:163]
	v_lshlrev_b32_e32 v162, 11, v10
	v_lshl_add_u64 v[8:9], v[6:7], 0, v[162:163]
	s_waitcnt lgkmcnt(0)
	global_store_dwordx4 v[8:9], v[2:5], off
	v_or_b32_e32 v8, 4, v10
	v_lshlrev_b32_e32 v162, 11, v8
	v_lshl_add_u32 v2, v8, 8, v11
	ds_read_b128 v[2:5], v2
	v_lshl_add_u64 v[8:9], v[6:7], 0, v[162:163]
	s_waitcnt lgkmcnt(0)
	global_store_dwordx4 v[8:9], v[2:5], off
	v_or_b32_e32 v8, 8, v10
	s_nop 0
	v_lshl_add_u32 v2, v8, 8, v11
	ds_read_b128 v[2:5], v2
	v_lshlrev_b32_e32 v162, 11, v8
	v_lshl_add_u64 v[8:9], v[6:7], 0, v[162:163]
	s_waitcnt lgkmcnt(0)
	global_store_dwordx4 v[8:9], v[2:5], off
	v_or_b32_e32 v8, 12, v10
	s_nop 0
	v_lshl_add_u32 v2, v8, 8, v11
	ds_read_b128 v[2:5], v2
	v_lshlrev_b32_e32 v162, 11, v8
	v_lshl_add_u64 v[8:9], v[6:7], 0, v[162:163]
	s_waitcnt lgkmcnt(0)
	global_store_dwordx4 v[8:9], v[2:5], off
	v_or_b32_e32 v8, 16, v10
	s_nop 0
	v_lshl_add_u32 v2, v8, 8, v11
	ds_read_b128 v[2:5], v2
	v_lshlrev_b32_e32 v162, 11, v8
	v_lshl_add_u64 v[8:9], v[6:7], 0, v[162:163]
	s_waitcnt lgkmcnt(0)
	global_store_dwordx4 v[8:9], v[2:5], off
	v_or_b32_e32 v8, 20, v10
	s_nop 0
	v_lshl_add_u32 v2, v8, 8, v11
	ds_read_b128 v[2:5], v2
	v_lshlrev_b32_e32 v162, 11, v8
	v_lshl_add_u64 v[8:9], v[6:7], 0, v[162:163]
	s_waitcnt lgkmcnt(0)
	global_store_dwordx4 v[8:9], v[2:5], off
	v_or_b32_e32 v8, 24, v10
	s_nop 0
	v_lshl_add_u32 v2, v8, 8, v11
	ds_read_b128 v[2:5], v2
	v_lshlrev_b32_e32 v162, 11, v8
	v_lshl_add_u64 v[8:9], v[6:7], 0, v[162:163]
	s_waitcnt lgkmcnt(0)
	global_store_dwordx4 v[8:9], v[2:5], off
	v_or_b32_e32 v8, 28, v10
	s_nop 0
	v_lshl_add_u32 v2, v8, 8, v11
	ds_read_b128 v[2:5], v2
	v_lshlrev_b32_e32 v162, 11, v8
	v_lshl_add_u64 v[6:7], v[6:7], 0, v[162:163]
	s_waitcnt lgkmcnt(0)
	global_store_dwordx4 v[6:7], v[2:5], off
	s_barrier
	s_and_saveexec_b64 s[0:1], s[36:37]
	s_cbranch_execz .LBB0_814
	s_waitcnt vmcnt(8)
	v_mov_b32_e32 v1, v247
	v_readlane_b32 s2, v243, 55
	s_nop 1
	v_mov_b32_e32 v2, s2
	ds_write_b32 v2, v1
	s_branch .LBB0_814
